# counted vmcnt waits at first use in EpiOut (P3) and EpiDown (P5) epilogues instead of vmcnt(0) after the load block
# speedup vs baseline: 1.0031x; 1.0031x over previous
.LBB0_649:
	v_lshl_or_b32 v202, s20, 8, v227
	v_lshl_add_u32 v230, s40, 8, v207
	v_ashrrev_i32_e32 v203, 31, v202
	v_lshlrev_b64 v[234:235], 1, v[202:203]
	v_ashrrev_i32_e32 v231, 31, v230
	v_lshl_add_u64 v[88:89], s[60:61], 0, v[234:235]
	v_lshlrev_b64 v[90:91], 11, v[230:231]
	v_readlane_b32 s42, v254, 17
	v_lshl_add_u64 v[90:91], v[88:89], 0, v[90:91]
	v_readlane_b32 s43, v254, 18
	global_load_dwordx4 v[240:243], v[90:91], off
	global_load_dwordx4 v[244:247], v[90:91], off offset:64
	v_lshl_add_u64 v[100:101], v[230:231], 2, s[42:43]
	global_load_dword v248, v[100:101], off
	v_or_b32_e32 v228, 16, v230
	v_or_b32_e32 v224, 32, v230
	v_or_b32_e32 v220, 48, v230
	v_add_u32_e32 v216, 0x80, v230
	v_add_u32_e32 v212, 0x90, v230
	v_add_u32_e32 v208, 0xa0, v230
	v_add_u32_e32 v204, 0xb0, v230
	v_ashrrev_i32_e32 v229, 31, v228
	v_ashrrev_i32_e32 v225, 31, v224
	v_ashrrev_i32_e32 v221, 31, v220
	v_ashrrev_i32_e32 v217, 31, v216
	v_ashrrev_i32_e32 v213, 31, v212
	v_ashrrev_i32_e32 v209, 31, v208
	v_ashrrev_i32_e32 v205, 31, v204
	v_lshlrev_b64 v[102:103], 11, v[228:229]
	v_lshlrev_b64 v[114:115], 11, v[224:225]
	v_lshlrev_b64 v[126:127], 11, v[220:221]
	v_lshlrev_b64 v[136:137], 11, v[216:217]
	v_lshlrev_b64 v[138:139], 11, v[212:213]
	v_lshlrev_b64 v[148:149], 11, v[208:209]
	global_load_dword v218, v[100:101], off offset:512
	global_load_dword v214, v[100:101], off offset:576
	global_load_dword v210, v[100:101], off offset:640
	global_load_dword v206, v[100:101], off offset:704
	v_lshlrev_b64 v[100:101], 11, v[204:205]
	v_lshl_add_u64 v[90:91], v[228:229], 2, s[42:43]
	v_lshl_add_u64 v[112:113], v[224:225], 2, s[42:43]
	v_lshl_add_u64 v[124:125], v[220:221], 2, s[42:43]
	v_lshl_add_u64 v[102:103], v[88:89], 0, v[102:103]
	v_lshl_add_u64 v[114:115], v[88:89], 0, v[114:115]
	v_lshl_add_u64 v[126:127], v[88:89], 0, v[126:127]
	v_lshl_add_u64 v[136:137], v[88:89], 0, v[136:137]
	v_lshl_add_u64 v[138:139], v[88:89], 0, v[138:139]
	v_lshl_add_u64 v[250:251], v[88:89], 0, v[148:149]
	v_lshl_add_u64 v[88:89], v[88:89], 0, v[100:101]
	global_load_dword v232, v[90:91], off
	global_load_dwordx4 v[180:183], v[102:103], off
	global_load_dwordx4 v[176:179], v[102:103], off offset:64
	global_load_dword v226, v[112:113], off
	global_load_dwordx4 v[172:175], v[114:115], off
	global_load_dwordx4 v[168:171], v[114:115], off offset:64
	global_load_dword v222, v[124:125], off
	global_load_dwordx4 v[164:167], v[126:127], off
	global_load_dwordx4 v[160:163], v[126:127], off offset:64
	global_load_dwordx4 v[156:159], v[136:137], off
	global_load_dwordx4 v[152:155], v[136:137], off offset:64
	global_load_dwordx4 v[148:151], v[138:139], off
	s_nop 0
	global_load_dwordx4 v[136:139], v[138:139], off offset:64
	s_nop 0
	global_load_dwordx4 v[124:127], v[250:251], off
	global_load_dwordx4 v[112:115], v[250:251], off offset:64
	global_load_dwordx4 v[100:103], v[88:89], off
	s_nop 0
	global_load_dwordx4 v[88:91], v[88:89], off offset:64
	s_lshl_b32 s40, s20, 2
	s_ashr_i32 s41, s40, 31
	s_waitcnt vmcnt(23)
	v_lshlrev_b32_e32 v250, 16, v240
	v_and_b32_e32 v251, 0xffff0000, v240
	v_lshlrev_b32_e32 v240, 16, v241
	v_and_b32_e32 v241, 0xffff0000, v241
	v_lshlrev_b32_e32 v252, 16, v242
	v_and_b32_e32 v253, 0xffff0000, v242
	s_waitcnt vmcnt(21)
	v_pk_fma_f32 v[146:147], v[248:249], v[240:241], v[146:147] op_sel_hi:[0,1,1]
	v_pk_fma_f32 v[144:145], v[248:249], v[250:251], v[144:145] op_sel_hi:[0,1,1]
	v_pk_fma_f32 v[140:141], v[248:249], v[252:253], v[140:141] op_sel_hi:[0,1,1]
	v_cvt_pk_bf16_f32 v239, v144, v145
	v_cvt_pk_bf16_f32 v240, v146, v147
	v_mul_f32_e32 v145, v145, v145
	v_mul_f32_e32 v147, v147, v147
	v_lshlrev_b32_e32 v242, 16, v243
	v_and_b32_e32 v243, 0xffff0000, v243
	v_cvt_pk_bf16_f32 v241, v140, v141
	v_mul_f32_e32 v141, v141, v141
	v_fmac_f32_e32 v145, v144, v144
	v_fmac_f32_e32 v147, v146, v146
	v_pk_fma_f32 v[142:143], v[248:249], v[242:243], v[142:143] op_sel_hi:[0,1,1]
	v_fmac_f32_e32 v141, v140, v140
	v_add_f32_e32 v140, v145, v147
	v_add_f32_e32 v140, v141, v140
	v_mul_f32_e32 v141, v143, v143
	v_fmac_f32_e32 v141, v142, v142
	v_add_f32_e32 v243, v141, v140
	s_waitcnt vmcnt(21)
	v_lshlrev_b32_e32 v140, 16, v244
	v_and_b32_e32 v141, 0xffff0000, v244
	v_cvt_pk_bf16_f32 v242, v142, v143
	v_lshlrev_b32_e32 v142, 16, v245
	v_and_b32_e32 v143, 0xffff0000, v245
	v_pk_fma_f32 v[132:133], v[248:249], v[140:141], v[132:133] op_sel_hi:[0,1,1]
	v_lshlrev_b32_e32 v144, 16, v246
	v_and_b32_e32 v145, 0xffff0000, v246
	v_pk_fma_f32 v[134:135], v[248:249], v[142:143], v[134:135] op_sel_hi:[0,1,1]
	v_cvt_pk_bf16_f32 v140, v132, v133
	v_mul_f32_e32 v133, v133, v133
	v_pk_fma_f32 v[128:129], v[248:249], v[144:145], v[128:129] op_sel_hi:[0,1,1]
	v_fmac_f32_e32 v133, v132, v132
	v_mul_f32_e32 v132, v135, v135
	v_lshlrev_b32_e32 v146, 16, v247
	v_and_b32_e32 v147, 0xffff0000, v247
	v_cvt_pk_bf16_f32 v141, v134, v135
	v_cvt_pk_bf16_f32 v142, v128, v129
	v_fmac_f32_e32 v132, v134, v134
	v_mul_f32_e32 v129, v129, v129
	v_pk_fma_f32 v[130:131], v[248:249], v[146:147], v[130:131] op_sel_hi:[0,1,1]
	v_add_f32_e32 v132, v133, v132
	v_fmac_f32_e32 v129, v128, v128
	v_add_f32_e32 v128, v129, v132
	v_mul_f32_e32 v129, v131, v131
	v_fmac_f32_e32 v129, v130, v130
	v_add_f32_e32 v128, v129, v128
	v_cvt_pk_bf16_f32 v143, v130, v131
	v_add_f32_e32 v132, v243, v128
	v_sub_u32_e32 v128, v230, v233
	v_cndmask_b32_e64 v129, v242, v143, s[6:7]
	ds_bpermute_b32 v147, v219, v132
	v_cndmask_b32_e64 v130, v241, v142, s[6:7]
	v_mov_b32_dpp v146, v129 quad_perm:[1,0,3,2] row_mask:0xf bank_mask:0xf bound_ctrl:1
	v_ashrrev_i32_e32 v129, 31, v128
	v_lshlrev_b64 v[128:129], 11, v[128:129]
	v_cndmask_b32_e64 v131, v240, v141, s[6:7]
	v_cndmask_b32_e64 v133, v239, v140, s[6:7]
	v_lshl_add_u64 v[128:129], s[14:15], 0, v[128:129]
	v_mov_b32_dpp v144, v131 quad_perm:[1,0,3,2] row_mask:0xf bank_mask:0xf bound_ctrl:1
	v_mov_b32_dpp v133, v133 quad_perm:[1,0,3,2] row_mask:0xf bank_mask:0xf bound_ctrl:1
	v_mov_b32_dpp v145, v130 quad_perm:[1,0,3,2] row_mask:0xf bank_mask:0xf bound_ctrl:1
	v_lshl_add_u64 v[128:129], v[128:129], 0, v[234:235]
	v_lshl_add_u64 v[134:135], v[128:129], 0, v[192:193]
	v_cndmask_b32_e64 v128, v133, v239, s[6:7]
	v_cndmask_b32_e64 v129, v144, v240, s[6:7]
	v_cndmask_b32_e64 v130, v145, v241, s[6:7]
	v_cndmask_b32_e64 v131, v146, v242, s[6:7]
	global_store_dwordx4 v[134:135], v[128:131], off
	s_waitcnt lgkmcnt(0)
	s_nop 0
	v_add_f32_e32 v128, v132, v147
	ds_bpermute_b32 v129, v223, v128
	v_cndmask_b32_e64 v130, v140, v133, s[6:7]
	v_cndmask_b32_e64 v131, v141, v144, s[6:7]
	v_cndmask_b32_e64 v132, v142, v145, s[6:7]
	v_cndmask_b32_e64 v133, v143, v146, s[6:7]
	global_store_dwordx4 v[134:135], v[130:133], off offset:2048
	s_and_saveexec_b64 s[42:43], s[0:1]
	s_cbranch_execz .LBB0_651
	v_lshlrev_b64 v[130:131], 6, v[230:231]
	v_lshl_add_u64 v[130:131], s[18:19], 0, v[130:131]
	v_lshl_add_u64 v[130:131], s[40:41], 2, v[130:131]
	s_lshl_b32 s20, s48, 2
	v_lshl_add_u64 v[130:131], v[130:131], 0, s[20:21]
	s_waitcnt lgkmcnt(0)
	v_add_f32_e32 v128, v128, v129
	global_store_dword v[130:131], v128, off
.LBB0_651:
	s_or_b64 exec, exec, s[42:43]
	s_waitcnt vmcnt(18)
	v_lshlrev_b32_e32 v128, 16, v180
	s_waitcnt lgkmcnt(0)
	v_and_b32_e32 v129, 0xffff0000, v180
	v_lshlrev_b32_e32 v130, 16, v181
	v_and_b32_e32 v131, 0xffff0000, v181
	s_waitcnt vmcnt(18)
	v_pk_fma_f32 v[120:121], v[232:233], v[128:129], v[120:121] op_sel_hi:[0,1,1]
	v_lshlrev_b32_e32 v132, 16, v182
	v_and_b32_e32 v133, 0xffff0000, v182
	v_pk_fma_f32 v[122:123], v[232:233], v[130:131], v[122:123] op_sel_hi:[0,1,1]
	v_cvt_pk_bf16_f32 v128, v120, v121
	v_mul_f32_e32 v121, v121, v121
	v_pk_fma_f32 v[116:117], v[232:233], v[132:133], v[116:117] op_sel_hi:[0,1,1]
	v_fmac_f32_e32 v121, v120, v120
	v_mul_f32_e32 v120, v123, v123
	v_lshlrev_b32_e32 v134, 16, v183
	v_and_b32_e32 v135, 0xffff0000, v183
	v_cvt_pk_bf16_f32 v129, v122, v123
	v_cvt_pk_bf16_f32 v130, v116, v117
	v_fmac_f32_e32 v120, v122, v122
	v_mul_f32_e32 v117, v117, v117
	v_pk_fma_f32 v[118:119], v[232:233], v[134:135], v[118:119] op_sel_hi:[0,1,1]
	v_add_f32_e32 v120, v121, v120
	v_fmac_f32_e32 v117, v116, v116
	v_add_f32_e32 v116, v117, v120
	v_mul_f32_e32 v117, v119, v119
	v_fmac_f32_e32 v117, v118, v118
	v_add_f32_e32 v132, v117, v116
	s_waitcnt vmcnt(17)
	v_lshlrev_b32_e32 v116, 16, v176
	v_and_b32_e32 v117, 0xffff0000, v176
	v_cvt_pk_bf16_f32 v131, v118, v119
	v_lshlrev_b32_e32 v118, 16, v177
	v_and_b32_e32 v119, 0xffff0000, v177
	v_pk_fma_f32 v[108:109], v[232:233], v[116:117], v[108:109] op_sel_hi:[0,1,1]
	v_lshlrev_b32_e32 v120, 16, v178
	v_and_b32_e32 v121, 0xffff0000, v178
	v_pk_fma_f32 v[110:111], v[232:233], v[118:119], v[110:111] op_sel_hi:[0,1,1]
	v_cvt_pk_bf16_f32 v116, v108, v109
	v_mul_f32_e32 v109, v109, v109
	v_pk_fma_f32 v[104:105], v[232:233], v[120:121], v[104:105] op_sel_hi:[0,1,1]
	v_fmac_f32_e32 v109, v108, v108
	v_mul_f32_e32 v108, v111, v111
	v_lshlrev_b32_e32 v122, 16, v179
	v_and_b32_e32 v123, 0xffff0000, v179
	v_cvt_pk_bf16_f32 v117, v110, v111
	v_cvt_pk_bf16_f32 v118, v104, v105
	v_fmac_f32_e32 v108, v110, v110
	v_mul_f32_e32 v105, v105, v105
	v_pk_fma_f32 v[106:107], v[232:233], v[122:123], v[106:107] op_sel_hi:[0,1,1]
	v_add_f32_e32 v108, v109, v108
	v_fmac_f32_e32 v105, v104, v104
	v_add_f32_e32 v104, v105, v108
	v_mul_f32_e32 v105, v107, v107
	v_fmac_f32_e32 v105, v106, v106
	v_add_f32_e32 v104, v105, v104
	v_cvt_pk_bf16_f32 v119, v106, v107
	v_add_f32_e32 v108, v132, v104
	v_sub_u32_e32 v104, v228, v233
	v_cndmask_b32_e64 v105, v131, v119, s[6:7]
	ds_bpermute_b32 v123, v219, v108
	v_cndmask_b32_e64 v106, v130, v118, s[6:7]
	v_mov_b32_dpp v122, v105 quad_perm:[1,0,3,2] row_mask:0xf bank_mask:0xf bound_ctrl:1
	v_ashrrev_i32_e32 v105, 31, v104
	v_lshlrev_b64 v[104:105], 11, v[104:105]
	v_cndmask_b32_e64 v107, v129, v117, s[6:7]
	v_cndmask_b32_e64 v109, v128, v116, s[6:7]
	v_lshl_add_u64 v[104:105], s[14:15], 0, v[104:105]
	v_mov_b32_dpp v120, v107 quad_perm:[1,0,3,2] row_mask:0xf bank_mask:0xf bound_ctrl:1
	v_mov_b32_dpp v109, v109 quad_perm:[1,0,3,2] row_mask:0xf bank_mask:0xf bound_ctrl:1
	v_mov_b32_dpp v121, v106 quad_perm:[1,0,3,2] row_mask:0xf bank_mask:0xf bound_ctrl:1
	v_lshl_add_u64 v[104:105], v[202:203], 1, v[104:105]
	v_lshl_add_u64 v[110:111], v[104:105], 0, v[192:193]
	v_cndmask_b32_e64 v104, v109, v128, s[6:7]
	v_cndmask_b32_e64 v105, v120, v129, s[6:7]
	v_cndmask_b32_e64 v106, v121, v130, s[6:7]
	v_cndmask_b32_e64 v107, v122, v131, s[6:7]
	global_store_dwordx4 v[110:111], v[104:107], off
	s_waitcnt lgkmcnt(0)
	s_nop 0
	v_add_f32_e32 v104, v108, v123
	ds_bpermute_b32 v105, v223, v104
	v_cndmask_b32_e64 v106, v116, v109, s[6:7]
	v_cndmask_b32_e64 v107, v117, v120, s[6:7]
	v_cndmask_b32_e64 v108, v118, v121, s[6:7]
	v_cndmask_b32_e64 v109, v119, v122, s[6:7]
	global_store_dwordx4 v[110:111], v[106:109], off offset:2048
	s_and_saveexec_b64 s[42:43], s[0:1]
	s_cbranch_execz .LBB0_653
	v_lshlrev_b64 v[106:107], 6, v[228:229]
	v_lshl_add_u64 v[106:107], s[18:19], 0, v[106:107]
	v_lshl_add_u64 v[106:107], s[40:41], 2, v[106:107]
	s_lshl_b32 s20, s48, 2
	v_lshl_add_u64 v[106:107], v[106:107], 0, s[20:21]
	s_waitcnt lgkmcnt(0)
	v_add_f32_e32 v104, v104, v105
	global_store_dword v[106:107], v104, off
.LBB0_653:
	s_or_b64 exec, exec, s[42:43]
	s_waitcnt vmcnt(18)
	v_lshlrev_b32_e32 v104, 16, v172
	s_waitcnt lgkmcnt(0)
	v_and_b32_e32 v105, 0xffff0000, v172
	v_lshlrev_b32_e32 v106, 16, v173
	v_and_b32_e32 v107, 0xffff0000, v173
	s_waitcnt vmcnt(18)
	v_pk_fma_f32 v[96:97], v[226:227], v[104:105], v[96:97] op_sel_hi:[0,1,1]
	v_lshlrev_b32_e32 v108, 16, v174
	v_and_b32_e32 v109, 0xffff0000, v174
	v_pk_fma_f32 v[98:99], v[226:227], v[106:107], v[98:99] op_sel_hi:[0,1,1]
	v_cvt_pk_bf16_f32 v104, v96, v97
	v_mul_f32_e32 v97, v97, v97
	v_pk_fma_f32 v[92:93], v[226:227], v[108:109], v[92:93] op_sel_hi:[0,1,1]
	v_fmac_f32_e32 v97, v96, v96
	v_mul_f32_e32 v96, v99, v99
	v_lshlrev_b32_e32 v110, 16, v175
	v_and_b32_e32 v111, 0xffff0000, v175
	v_cvt_pk_bf16_f32 v105, v98, v99
	v_cvt_pk_bf16_f32 v106, v92, v93
	v_fmac_f32_e32 v96, v98, v98
	v_mul_f32_e32 v93, v93, v93
	v_pk_fma_f32 v[94:95], v[226:227], v[110:111], v[94:95] op_sel_hi:[0,1,1]
	v_add_f32_e32 v96, v97, v96
	v_fmac_f32_e32 v93, v92, v92
	v_add_f32_e32 v92, v93, v96
	v_mul_f32_e32 v93, v95, v95
	v_fmac_f32_e32 v93, v94, v94
	v_add_f32_e32 v108, v93, v92
	s_waitcnt vmcnt(17)
	v_lshlrev_b32_e32 v92, 16, v168
	v_and_b32_e32 v93, 0xffff0000, v168
	v_cvt_pk_bf16_f32 v107, v94, v95
	v_lshlrev_b32_e32 v94, 16, v169
	v_and_b32_e32 v95, 0xffff0000, v169
	v_pk_fma_f32 v[84:85], v[226:227], v[92:93], v[84:85] op_sel_hi:[0,1,1]
	v_lshlrev_b32_e32 v96, 16, v170
	v_and_b32_e32 v97, 0xffff0000, v170
	v_pk_fma_f32 v[86:87], v[226:227], v[94:95], v[86:87] op_sel_hi:[0,1,1]
	v_cvt_pk_bf16_f32 v92, v84, v85
	v_mul_f32_e32 v85, v85, v85
	v_pk_fma_f32 v[80:81], v[226:227], v[96:97], v[80:81] op_sel_hi:[0,1,1]
	v_fmac_f32_e32 v85, v84, v84
	v_mul_f32_e32 v84, v87, v87
	v_lshlrev_b32_e32 v98, 16, v171
	v_and_b32_e32 v99, 0xffff0000, v171
	v_cvt_pk_bf16_f32 v93, v86, v87
	v_cvt_pk_bf16_f32 v94, v80, v81
	v_fmac_f32_e32 v84, v86, v86
	v_mul_f32_e32 v81, v81, v81
	v_pk_fma_f32 v[82:83], v[226:227], v[98:99], v[82:83] op_sel_hi:[0,1,1]
	v_add_f32_e32 v84, v85, v84
	v_fmac_f32_e32 v81, v80, v80
	v_add_f32_e32 v80, v81, v84
	v_mul_f32_e32 v81, v83, v83
	v_fmac_f32_e32 v81, v82, v82
	v_add_f32_e32 v80, v81, v80
	v_cvt_pk_bf16_f32 v95, v82, v83
	v_add_f32_e32 v84, v108, v80
	v_sub_u32_e32 v80, v224, v233
	v_cndmask_b32_e64 v81, v107, v95, s[6:7]
	ds_bpermute_b32 v99, v219, v84
	v_cndmask_b32_e64 v82, v106, v94, s[6:7]
	v_mov_b32_dpp v98, v81 quad_perm:[1,0,3,2] row_mask:0xf bank_mask:0xf bound_ctrl:1
	v_ashrrev_i32_e32 v81, 31, v80
	v_lshlrev_b64 v[80:81], 11, v[80:81]
	v_cndmask_b32_e64 v83, v105, v93, s[6:7]
	v_cndmask_b32_e64 v85, v104, v92, s[6:7]
	v_lshl_add_u64 v[80:81], s[14:15], 0, v[80:81]
	v_mov_b32_dpp v96, v83 quad_perm:[1,0,3,2] row_mask:0xf bank_mask:0xf bound_ctrl:1
	v_mov_b32_dpp v85, v85 quad_perm:[1,0,3,2] row_mask:0xf bank_mask:0xf bound_ctrl:1
	v_mov_b32_dpp v97, v82 quad_perm:[1,0,3,2] row_mask:0xf bank_mask:0xf bound_ctrl:1
	v_lshl_add_u64 v[80:81], v[202:203], 1, v[80:81]
	v_lshl_add_u64 v[86:87], v[80:81], 0, v[192:193]
	v_cndmask_b32_e64 v80, v85, v104, s[6:7]
	v_cndmask_b32_e64 v81, v96, v105, s[6:7]
	v_cndmask_b32_e64 v82, v97, v106, s[6:7]
	v_cndmask_b32_e64 v83, v98, v107, s[6:7]
	global_store_dwordx4 v[86:87], v[80:83], off
	s_waitcnt lgkmcnt(0)
	s_nop 0
	v_add_f32_e32 v80, v84, v99
	ds_bpermute_b32 v81, v223, v80
	v_cndmask_b32_e64 v82, v92, v85, s[6:7]
	v_cndmask_b32_e64 v83, v93, v96, s[6:7]
	v_cndmask_b32_e64 v84, v94, v97, s[6:7]
	v_cndmask_b32_e64 v85, v95, v98, s[6:7]
	global_store_dwordx4 v[86:87], v[82:85], off offset:2048
	s_and_saveexec_b64 s[42:43], s[0:1]
	s_cbranch_execz .LBB0_655
	v_lshlrev_b64 v[82:83], 6, v[224:225]
	v_lshl_add_u64 v[82:83], s[18:19], 0, v[82:83]
	v_lshl_add_u64 v[82:83], s[40:41], 2, v[82:83]
	s_lshl_b32 s20, s48, 2
	v_lshl_add_u64 v[82:83], v[82:83], 0, s[20:21]
	s_waitcnt lgkmcnt(0)
	v_add_f32_e32 v80, v80, v81
	global_store_dword v[82:83], v80, off
.LBB0_655:
	s_or_b64 exec, exec, s[42:43]
	s_waitcnt vmcnt(18)
	v_lshlrev_b32_e32 v80, 16, v164
	s_waitcnt lgkmcnt(0)
	v_and_b32_e32 v81, 0xffff0000, v164
	v_lshlrev_b32_e32 v82, 16, v165
	v_and_b32_e32 v83, 0xffff0000, v165
	s_waitcnt vmcnt(18)
	v_pk_fma_f32 v[76:77], v[222:223], v[80:81], v[76:77] op_sel_hi:[0,1,1]
	v_lshlrev_b32_e32 v84, 16, v166
	v_and_b32_e32 v85, 0xffff0000, v166
	v_pk_fma_f32 v[78:79], v[222:223], v[82:83], v[78:79] op_sel_hi:[0,1,1]
	v_cvt_pk_bf16_f32 v80, v76, v77
	v_mul_f32_e32 v77, v77, v77
	v_pk_fma_f32 v[72:73], v[222:223], v[84:85], v[72:73] op_sel_hi:[0,1,1]
	v_fmac_f32_e32 v77, v76, v76
	v_mul_f32_e32 v76, v79, v79
	v_lshlrev_b32_e32 v86, 16, v167
	v_and_b32_e32 v87, 0xffff0000, v167
	v_cvt_pk_bf16_f32 v81, v78, v79
	v_cvt_pk_bf16_f32 v82, v72, v73
	v_fmac_f32_e32 v76, v78, v78
	v_mul_f32_e32 v73, v73, v73
	v_pk_fma_f32 v[74:75], v[222:223], v[86:87], v[74:75] op_sel_hi:[0,1,1]
	v_add_f32_e32 v76, v77, v76
	v_fmac_f32_e32 v73, v72, v72
	v_add_f32_e32 v72, v73, v76
	v_mul_f32_e32 v73, v75, v75
	v_fmac_f32_e32 v73, v74, v74
	v_add_f32_e32 v84, v73, v72
	s_waitcnt vmcnt(17)
	v_lshlrev_b32_e32 v72, 16, v160
	v_and_b32_e32 v73, 0xffff0000, v160
	v_cvt_pk_bf16_f32 v83, v74, v75
	v_lshlrev_b32_e32 v74, 16, v161
	v_and_b32_e32 v75, 0xffff0000, v161
	v_pk_fma_f32 v[68:69], v[222:223], v[72:73], v[68:69] op_sel_hi:[0,1,1]
	v_lshlrev_b32_e32 v76, 16, v162
	v_and_b32_e32 v77, 0xffff0000, v162
	v_pk_fma_f32 v[70:71], v[222:223], v[74:75], v[70:71] op_sel_hi:[0,1,1]
	v_cvt_pk_bf16_f32 v72, v68, v69
	v_mul_f32_e32 v69, v69, v69
	v_pk_fma_f32 v[64:65], v[222:223], v[76:77], v[64:65] op_sel_hi:[0,1,1]
	v_fmac_f32_e32 v69, v68, v68
	v_mul_f32_e32 v68, v71, v71
	v_lshlrev_b32_e32 v78, 16, v163
	v_and_b32_e32 v79, 0xffff0000, v163
	v_cvt_pk_bf16_f32 v73, v70, v71
	v_cvt_pk_bf16_f32 v74, v64, v65
	v_fmac_f32_e32 v68, v70, v70
	v_mul_f32_e32 v65, v65, v65
	v_pk_fma_f32 v[66:67], v[222:223], v[78:79], v[66:67] op_sel_hi:[0,1,1]
	v_add_f32_e32 v68, v69, v68
	v_fmac_f32_e32 v65, v64, v64
	v_add_f32_e32 v64, v65, v68
	v_mul_f32_e32 v65, v67, v67
	v_fmac_f32_e32 v65, v66, v66
	v_add_f32_e32 v64, v65, v64
	v_cvt_pk_bf16_f32 v75, v66, v67
	v_add_f32_e32 v68, v84, v64
	v_sub_u32_e32 v64, v220, v233
	v_cndmask_b32_e64 v65, v83, v75, s[6:7]
	ds_bpermute_b32 v79, v219, v68
	v_cndmask_b32_e64 v66, v82, v74, s[6:7]
	v_mov_b32_dpp v78, v65 quad_perm:[1,0,3,2] row_mask:0xf bank_mask:0xf bound_ctrl:1
	v_ashrrev_i32_e32 v65, 31, v64
	v_lshlrev_b64 v[64:65], 11, v[64:65]
	v_cndmask_b32_e64 v67, v81, v73, s[6:7]
	v_cndmask_b32_e64 v69, v80, v72, s[6:7]
	v_lshl_add_u64 v[64:65], s[14:15], 0, v[64:65]
	v_mov_b32_dpp v76, v67 quad_perm:[1,0,3,2] row_mask:0xf bank_mask:0xf bound_ctrl:1
	v_mov_b32_dpp v69, v69 quad_perm:[1,0,3,2] row_mask:0xf bank_mask:0xf bound_ctrl:1
	v_mov_b32_dpp v77, v66 quad_perm:[1,0,3,2] row_mask:0xf bank_mask:0xf bound_ctrl:1
	v_lshl_add_u64 v[64:65], v[202:203], 1, v[64:65]
	v_lshl_add_u64 v[70:71], v[64:65], 0, v[192:193]
	v_cndmask_b32_e64 v64, v69, v80, s[6:7]
	v_cndmask_b32_e64 v65, v76, v81, s[6:7]
	v_cndmask_b32_e64 v66, v77, v82, s[6:7]
	v_cndmask_b32_e64 v67, v78, v83, s[6:7]
	global_store_dwordx4 v[70:71], v[64:67], off
	s_waitcnt lgkmcnt(0)
	s_nop 0
	v_add_f32_e32 v64, v68, v79
	ds_bpermute_b32 v65, v223, v64
	v_cndmask_b32_e64 v66, v72, v69, s[6:7]
	v_cndmask_b32_e64 v67, v73, v76, s[6:7]
	v_cndmask_b32_e64 v68, v74, v77, s[6:7]
	v_cndmask_b32_e64 v69, v75, v78, s[6:7]
	global_store_dwordx4 v[70:71], v[66:69], off offset:2048
	s_and_saveexec_b64 s[42:43], s[0:1]
	s_cbranch_execz .LBB0_657
	v_lshlrev_b64 v[66:67], 6, v[220:221]
	v_lshl_add_u64 v[66:67], s[18:19], 0, v[66:67]
	v_lshl_add_u64 v[66:67], s[40:41], 2, v[66:67]
	s_lshl_b32 s20, s48, 2
	v_lshl_add_u64 v[66:67], v[66:67], 0, s[20:21]
	s_waitcnt lgkmcnt(0)
	v_add_f32_e32 v64, v64, v65
	global_store_dword v[66:67], v64, off
.LBB0_657:
	s_or_b64 exec, exec, s[42:43]
	s_waitcnt vmcnt(19)
	v_lshlrev_b32_e32 v64, 16, v156
	s_waitcnt lgkmcnt(0)
	v_and_b32_e32 v65, 0xffff0000, v156
	v_lshlrev_b32_e32 v66, 16, v157
	v_and_b32_e32 v67, 0xffff0000, v157
	s_waitcnt vmcnt(19)
	v_pk_fma_f32 v[60:61], v[218:219], v[64:65], v[60:61] op_sel_hi:[0,1,1]
	v_lshlrev_b32_e32 v68, 16, v158
	v_and_b32_e32 v69, 0xffff0000, v158
	v_pk_fma_f32 v[62:63], v[218:219], v[66:67], v[62:63] op_sel_hi:[0,1,1]
	v_cvt_pk_bf16_f32 v64, v60, v61
	v_mul_f32_e32 v61, v61, v61
	v_pk_fma_f32 v[56:57], v[218:219], v[68:69], v[56:57] op_sel_hi:[0,1,1]
	v_fmac_f32_e32 v61, v60, v60
	v_mul_f32_e32 v60, v63, v63
	v_lshlrev_b32_e32 v70, 16, v159
	v_and_b32_e32 v71, 0xffff0000, v159
	v_cvt_pk_bf16_f32 v65, v62, v63
	v_cvt_pk_bf16_f32 v66, v56, v57
	v_fmac_f32_e32 v60, v62, v62
	v_mul_f32_e32 v57, v57, v57
	v_pk_fma_f32 v[58:59], v[218:219], v[70:71], v[58:59] op_sel_hi:[0,1,1]
	v_add_f32_e32 v60, v61, v60
	v_fmac_f32_e32 v57, v56, v56
	v_add_f32_e32 v56, v57, v60
	v_mul_f32_e32 v57, v59, v59
	v_fmac_f32_e32 v57, v58, v58
	v_add_f32_e32 v68, v57, v56
	s_waitcnt vmcnt(18)
	v_lshlrev_b32_e32 v56, 16, v152
	v_and_b32_e32 v57, 0xffff0000, v152
	v_cvt_pk_bf16_f32 v67, v58, v59
	v_lshlrev_b32_e32 v58, 16, v153
	v_and_b32_e32 v59, 0xffff0000, v153
	v_pk_fma_f32 v[52:53], v[218:219], v[56:57], v[52:53] op_sel_hi:[0,1,1]
	v_lshlrev_b32_e32 v60, 16, v154
	v_and_b32_e32 v61, 0xffff0000, v154
	v_pk_fma_f32 v[54:55], v[218:219], v[58:59], v[54:55] op_sel_hi:[0,1,1]
	v_cvt_pk_bf16_f32 v56, v52, v53
	v_mul_f32_e32 v53, v53, v53
	v_pk_fma_f32 v[48:49], v[218:219], v[60:61], v[48:49] op_sel_hi:[0,1,1]
	v_fmac_f32_e32 v53, v52, v52
	v_mul_f32_e32 v52, v55, v55
	v_lshlrev_b32_e32 v62, 16, v155
	v_and_b32_e32 v63, 0xffff0000, v155
	v_cvt_pk_bf16_f32 v57, v54, v55
	v_cvt_pk_bf16_f32 v58, v48, v49
	v_fmac_f32_e32 v52, v54, v54
	v_mul_f32_e32 v49, v49, v49
	v_pk_fma_f32 v[50:51], v[218:219], v[62:63], v[50:51] op_sel_hi:[0,1,1]
	v_add_f32_e32 v52, v53, v52
	v_fmac_f32_e32 v49, v48, v48
	v_add_f32_e32 v48, v49, v52
	v_mul_f32_e32 v49, v51, v51
	v_fmac_f32_e32 v49, v50, v50
	v_add_f32_e32 v48, v49, v48
	v_cvt_pk_bf16_f32 v59, v50, v51
	v_add_f32_e32 v52, v68, v48
	v_sub_u32_e32 v48, v216, v233
	v_cndmask_b32_e64 v49, v67, v59, s[6:7]
	ds_bpermute_b32 v63, v219, v52
	v_cndmask_b32_e64 v50, v66, v58, s[6:7]
	v_mov_b32_dpp v62, v49 quad_perm:[1,0,3,2] row_mask:0xf bank_mask:0xf bound_ctrl:1
	v_ashrrev_i32_e32 v49, 31, v48
	v_lshlrev_b64 v[48:49], 11, v[48:49]
	v_cndmask_b32_e64 v51, v65, v57, s[6:7]
	v_cndmask_b32_e64 v53, v64, v56, s[6:7]
	v_lshl_add_u64 v[48:49], s[14:15], 0, v[48:49]
	v_mov_b32_dpp v60, v51 quad_perm:[1,0,3,2] row_mask:0xf bank_mask:0xf bound_ctrl:1
	v_mov_b32_dpp v53, v53 quad_perm:[1,0,3,2] row_mask:0xf bank_mask:0xf bound_ctrl:1
	v_mov_b32_dpp v61, v50 quad_perm:[1,0,3,2] row_mask:0xf bank_mask:0xf bound_ctrl:1
	v_lshl_add_u64 v[48:49], v[202:203], 1, v[48:49]
	v_lshl_add_u64 v[54:55], v[48:49], 0, v[192:193]
	v_cndmask_b32_e64 v48, v53, v64, s[6:7]
	v_cndmask_b32_e64 v49, v60, v65, s[6:7]
	v_cndmask_b32_e64 v50, v61, v66, s[6:7]
	v_cndmask_b32_e64 v51, v62, v67, s[6:7]
	global_store_dwordx4 v[54:55], v[48:51], off
	s_waitcnt lgkmcnt(0)
	s_nop 0
	v_add_f32_e32 v48, v52, v63
	ds_bpermute_b32 v49, v223, v48
	v_cndmask_b32_e64 v50, v56, v53, s[6:7]
	v_cndmask_b32_e64 v51, v57, v60, s[6:7]
	v_cndmask_b32_e64 v52, v58, v61, s[6:7]
	v_cndmask_b32_e64 v53, v59, v62, s[6:7]
	global_store_dwordx4 v[54:55], v[50:53], off offset:2048
	s_and_saveexec_b64 s[42:43], s[0:1]
	s_cbranch_execz .LBB0_659
	v_lshlrev_b64 v[50:51], 6, v[216:217]
	v_lshl_add_u64 v[50:51], s[18:19], 0, v[50:51]
	v_lshl_add_u64 v[50:51], s[40:41], 2, v[50:51]
	s_lshl_b32 s20, s48, 2
	v_lshl_add_u64 v[50:51], v[50:51], 0, s[20:21]
	s_waitcnt lgkmcnt(0)
	v_add_f32_e32 v48, v48, v49
	global_store_dword v[50:51], v48, off
.LBB0_659:
	s_or_b64 exec, exec, s[42:43]
	s_waitcnt vmcnt(20)
	v_lshlrev_b32_e32 v48, 16, v148
	s_waitcnt lgkmcnt(0)
	v_and_b32_e32 v49, 0xffff0000, v148
	v_lshlrev_b32_e32 v50, 16, v149
	v_and_b32_e32 v51, 0xffff0000, v149
	s_waitcnt vmcnt(20)
	v_pk_fma_f32 v[44:45], v[214:215], v[48:49], v[44:45] op_sel_hi:[0,1,1]
	v_lshlrev_b32_e32 v52, 16, v150
	v_and_b32_e32 v53, 0xffff0000, v150
	v_pk_fma_f32 v[46:47], v[214:215], v[50:51], v[46:47] op_sel_hi:[0,1,1]
	v_cvt_pk_bf16_f32 v48, v44, v45
	v_mul_f32_e32 v45, v45, v45
	v_pk_fma_f32 v[40:41], v[214:215], v[52:53], v[40:41] op_sel_hi:[0,1,1]
	v_fmac_f32_e32 v45, v44, v44
	v_mul_f32_e32 v44, v47, v47
	v_lshlrev_b32_e32 v54, 16, v151
	v_and_b32_e32 v55, 0xffff0000, v151
	v_cvt_pk_bf16_f32 v49, v46, v47
	v_cvt_pk_bf16_f32 v50, v40, v41
	v_fmac_f32_e32 v44, v46, v46
	v_mul_f32_e32 v41, v41, v41
	v_pk_fma_f32 v[42:43], v[214:215], v[54:55], v[42:43] op_sel_hi:[0,1,1]
	v_add_f32_e32 v44, v45, v44
	v_fmac_f32_e32 v41, v40, v40
	v_add_f32_e32 v40, v41, v44
	v_mul_f32_e32 v41, v43, v43
	v_fmac_f32_e32 v41, v42, v42
	v_add_f32_e32 v52, v41, v40
	s_waitcnt vmcnt(19)
	v_lshlrev_b32_e32 v40, 16, v136
	v_and_b32_e32 v41, 0xffff0000, v136
	v_cvt_pk_bf16_f32 v51, v42, v43
	v_lshlrev_b32_e32 v42, 16, v137
	v_and_b32_e32 v43, 0xffff0000, v137
	v_pk_fma_f32 v[36:37], v[214:215], v[40:41], v[36:37] op_sel_hi:[0,1,1]
	v_lshlrev_b32_e32 v44, 16, v138
	v_and_b32_e32 v45, 0xffff0000, v138
	v_pk_fma_f32 v[38:39], v[214:215], v[42:43], v[38:39] op_sel_hi:[0,1,1]
	v_cvt_pk_bf16_f32 v40, v36, v37
	v_mul_f32_e32 v37, v37, v37
	v_pk_fma_f32 v[32:33], v[214:215], v[44:45], v[32:33] op_sel_hi:[0,1,1]
	v_fmac_f32_e32 v37, v36, v36
	v_mul_f32_e32 v36, v39, v39
	v_lshlrev_b32_e32 v46, 16, v139
	v_and_b32_e32 v47, 0xffff0000, v139
	v_cvt_pk_bf16_f32 v41, v38, v39
	v_cvt_pk_bf16_f32 v42, v32, v33
	v_fmac_f32_e32 v36, v38, v38
	v_mul_f32_e32 v33, v33, v33
	v_pk_fma_f32 v[34:35], v[214:215], v[46:47], v[34:35] op_sel_hi:[0,1,1]
	v_add_f32_e32 v36, v37, v36
	v_fmac_f32_e32 v33, v32, v32
	v_add_f32_e32 v32, v33, v36
	v_mul_f32_e32 v33, v35, v35
	v_fmac_f32_e32 v33, v34, v34
	v_add_f32_e32 v32, v33, v32
	v_cvt_pk_bf16_f32 v43, v34, v35
	v_add_f32_e32 v36, v52, v32
	v_sub_u32_e32 v32, v212, v233
	v_cndmask_b32_e64 v33, v51, v43, s[6:7]
	ds_bpermute_b32 v47, v219, v36
	v_cndmask_b32_e64 v34, v50, v42, s[6:7]
	v_mov_b32_dpp v46, v33 quad_perm:[1,0,3,2] row_mask:0xf bank_mask:0xf bound_ctrl:1
	v_ashrrev_i32_e32 v33, 31, v32
	v_lshlrev_b64 v[32:33], 11, v[32:33]
	v_cndmask_b32_e64 v35, v49, v41, s[6:7]
	v_cndmask_b32_e64 v37, v48, v40, s[6:7]
	v_lshl_add_u64 v[32:33], s[14:15], 0, v[32:33]
	v_mov_b32_dpp v44, v35 quad_perm:[1,0,3,2] row_mask:0xf bank_mask:0xf bound_ctrl:1
	v_mov_b32_dpp v37, v37 quad_perm:[1,0,3,2] row_mask:0xf bank_mask:0xf bound_ctrl:1
	v_mov_b32_dpp v45, v34 quad_perm:[1,0,3,2] row_mask:0xf bank_mask:0xf bound_ctrl:1
	v_lshl_add_u64 v[32:33], v[202:203], 1, v[32:33]
	v_lshl_add_u64 v[38:39], v[32:33], 0, v[192:193]
	v_cndmask_b32_e64 v32, v37, v48, s[6:7]
	v_cndmask_b32_e64 v33, v44, v49, s[6:7]
	v_cndmask_b32_e64 v34, v45, v50, s[6:7]
	v_cndmask_b32_e64 v35, v46, v51, s[6:7]
	global_store_dwordx4 v[38:39], v[32:35], off
	s_waitcnt lgkmcnt(0)
	s_nop 0
	v_add_f32_e32 v32, v36, v47
	ds_bpermute_b32 v33, v223, v32
	v_cndmask_b32_e64 v34, v40, v37, s[6:7]
	v_cndmask_b32_e64 v35, v41, v44, s[6:7]
	v_cndmask_b32_e64 v36, v42, v45, s[6:7]
	v_cndmask_b32_e64 v37, v43, v46, s[6:7]
	global_store_dwordx4 v[38:39], v[34:37], off offset:2048
	s_and_saveexec_b64 s[42:43], s[0:1]
	s_cbranch_execz .LBB0_661
	v_lshlrev_b64 v[34:35], 6, v[212:213]
	v_lshl_add_u64 v[34:35], s[18:19], 0, v[34:35]
	v_lshl_add_u64 v[34:35], s[40:41], 2, v[34:35]
	s_lshl_b32 s20, s48, 2
	v_lshl_add_u64 v[34:35], v[34:35], 0, s[20:21]
	s_waitcnt lgkmcnt(0)
	v_add_f32_e32 v32, v32, v33
	global_store_dword v[34:35], v32, off
.LBB0_661:
	s_or_b64 exec, exec, s[42:43]
	s_waitcnt vmcnt(21)
	v_lshlrev_b32_e32 v32, 16, v124
	s_waitcnt lgkmcnt(0)
	v_and_b32_e32 v33, 0xffff0000, v124
	v_lshlrev_b32_e32 v34, 16, v125
	v_and_b32_e32 v35, 0xffff0000, v125
	s_waitcnt vmcnt(21)
	v_pk_fma_f32 v[28:29], v[210:211], v[32:33], v[28:29] op_sel_hi:[0,1,1]
	v_lshlrev_b32_e32 v36, 16, v126
	v_and_b32_e32 v37, 0xffff0000, v126
	v_pk_fma_f32 v[30:31], v[210:211], v[34:35], v[30:31] op_sel_hi:[0,1,1]
	v_cvt_pk_bf16_f32 v32, v28, v29
	v_mul_f32_e32 v29, v29, v29
	v_pk_fma_f32 v[24:25], v[210:211], v[36:37], v[24:25] op_sel_hi:[0,1,1]
	v_fmac_f32_e32 v29, v28, v28
	v_mul_f32_e32 v28, v31, v31
	v_lshlrev_b32_e32 v38, 16, v127
	v_and_b32_e32 v39, 0xffff0000, v127
	v_cvt_pk_bf16_f32 v33, v30, v31
	v_cvt_pk_bf16_f32 v34, v24, v25
	v_fmac_f32_e32 v28, v30, v30
	v_mul_f32_e32 v25, v25, v25
	v_pk_fma_f32 v[26:27], v[210:211], v[38:39], v[26:27] op_sel_hi:[0,1,1]
	v_add_f32_e32 v28, v29, v28
	v_fmac_f32_e32 v25, v24, v24
	v_add_f32_e32 v24, v25, v28
	v_mul_f32_e32 v25, v27, v27
	v_fmac_f32_e32 v25, v26, v26
	v_add_f32_e32 v36, v25, v24
	s_waitcnt vmcnt(20)
	v_lshlrev_b32_e32 v24, 16, v112
	v_and_b32_e32 v25, 0xffff0000, v112
	v_cvt_pk_bf16_f32 v35, v26, v27
	v_lshlrev_b32_e32 v26, 16, v113
	v_and_b32_e32 v27, 0xffff0000, v113
	v_pk_fma_f32 v[20:21], v[210:211], v[24:25], v[20:21] op_sel_hi:[0,1,1]
	v_lshlrev_b32_e32 v28, 16, v114
	v_and_b32_e32 v29, 0xffff0000, v114
	v_pk_fma_f32 v[22:23], v[210:211], v[26:27], v[22:23] op_sel_hi:[0,1,1]
	v_cvt_pk_bf16_f32 v24, v20, v21
	v_mul_f32_e32 v21, v21, v21
	v_pk_fma_f32 v[16:17], v[210:211], v[28:29], v[16:17] op_sel_hi:[0,1,1]
	v_fmac_f32_e32 v21, v20, v20
	v_mul_f32_e32 v20, v23, v23
	v_lshlrev_b32_e32 v30, 16, v115
	v_and_b32_e32 v31, 0xffff0000, v115
	v_cvt_pk_bf16_f32 v25, v22, v23
	v_cvt_pk_bf16_f32 v26, v16, v17
	v_fmac_f32_e32 v20, v22, v22
	v_mul_f32_e32 v17, v17, v17
	v_pk_fma_f32 v[18:19], v[210:211], v[30:31], v[18:19] op_sel_hi:[0,1,1]
	v_add_f32_e32 v20, v21, v20
	v_fmac_f32_e32 v17, v16, v16
	v_add_f32_e32 v16, v17, v20
	v_mul_f32_e32 v17, v19, v19
	v_fmac_f32_e32 v17, v18, v18
	v_add_f32_e32 v16, v17, v16
	v_cvt_pk_bf16_f32 v27, v18, v19
	v_add_f32_e32 v20, v36, v16
	v_sub_u32_e32 v16, v208, v233
	v_cndmask_b32_e64 v17, v35, v27, s[6:7]
	ds_bpermute_b32 v31, v219, v20
	v_cndmask_b32_e64 v18, v34, v26, s[6:7]
	v_mov_b32_dpp v30, v17 quad_perm:[1,0,3,2] row_mask:0xf bank_mask:0xf bound_ctrl:1
	v_ashrrev_i32_e32 v17, 31, v16
	v_lshlrev_b64 v[16:17], 11, v[16:17]
	v_cndmask_b32_e64 v19, v33, v25, s[6:7]
	v_cndmask_b32_e64 v21, v32, v24, s[6:7]
	v_lshl_add_u64 v[16:17], s[14:15], 0, v[16:17]
	v_mov_b32_dpp v28, v19 quad_perm:[1,0,3,2] row_mask:0xf bank_mask:0xf bound_ctrl:1
	v_mov_b32_dpp v21, v21 quad_perm:[1,0,3,2] row_mask:0xf bank_mask:0xf bound_ctrl:1
	v_mov_b32_dpp v29, v18 quad_perm:[1,0,3,2] row_mask:0xf bank_mask:0xf bound_ctrl:1
	v_lshl_add_u64 v[16:17], v[202:203], 1, v[16:17]
	v_lshl_add_u64 v[22:23], v[16:17], 0, v[192:193]
	v_cndmask_b32_e64 v16, v21, v32, s[6:7]
	v_cndmask_b32_e64 v17, v28, v33, s[6:7]
	v_cndmask_b32_e64 v18, v29, v34, s[6:7]
	v_cndmask_b32_e64 v19, v30, v35, s[6:7]
	global_store_dwordx4 v[22:23], v[16:19], off
	s_waitcnt lgkmcnt(0)
	s_nop 0
	v_add_f32_e32 v16, v20, v31
	ds_bpermute_b32 v17, v223, v16
	v_cndmask_b32_e64 v18, v24, v21, s[6:7]
	v_cndmask_b32_e64 v19, v25, v28, s[6:7]
	v_cndmask_b32_e64 v20, v26, v29, s[6:7]
	v_cndmask_b32_e64 v21, v27, v30, s[6:7]
	global_store_dwordx4 v[22:23], v[18:21], off offset:2048
	s_and_saveexec_b64 s[42:43], s[0:1]
	s_cbranch_execz .LBB0_663
	v_lshlrev_b64 v[18:19], 6, v[208:209]
	v_lshl_add_u64 v[18:19], s[18:19], 0, v[18:19]
	v_lshl_add_u64 v[18:19], s[40:41], 2, v[18:19]
	s_lshl_b32 s20, s48, 2
	v_lshl_add_u64 v[18:19], v[18:19], 0, s[20:21]
	s_waitcnt lgkmcnt(0)
	v_add_f32_e32 v16, v16, v17
	global_store_dword v[18:19], v16, off
.LBB0_663:
	s_or_b64 exec, exec, s[42:43]
	s_waitcnt vmcnt(22)
	v_lshlrev_b32_e32 v16, 16, v100
	s_waitcnt lgkmcnt(0)
	v_and_b32_e32 v17, 0xffff0000, v100
	v_lshlrev_b32_e32 v18, 16, v101
	v_and_b32_e32 v19, 0xffff0000, v101
	s_waitcnt vmcnt(22)
	v_pk_fma_f32 v[12:13], v[206:207], v[16:17], v[12:13] op_sel_hi:[0,1,1]
	v_lshlrev_b32_e32 v20, 16, v102
	v_and_b32_e32 v21, 0xffff0000, v102
	v_pk_fma_f32 v[14:15], v[206:207], v[18:19], v[14:15] op_sel_hi:[0,1,1]
	v_cvt_pk_bf16_f32 v16, v12, v13
	v_mul_f32_e32 v13, v13, v13
	v_pk_fma_f32 v[8:9], v[206:207], v[20:21], v[8:9] op_sel_hi:[0,1,1]
	v_fmac_f32_e32 v13, v12, v12
	v_mul_f32_e32 v12, v15, v15
	v_lshlrev_b32_e32 v22, 16, v103
	v_and_b32_e32 v23, 0xffff0000, v103
	v_cvt_pk_bf16_f32 v17, v14, v15
	v_cvt_pk_bf16_f32 v18, v8, v9
	v_fmac_f32_e32 v12, v14, v14
	v_mul_f32_e32 v9, v9, v9
	v_pk_fma_f32 v[10:11], v[206:207], v[22:23], v[10:11] op_sel_hi:[0,1,1]
	v_add_f32_e32 v12, v13, v12
	v_fmac_f32_e32 v9, v8, v8
	v_add_f32_e32 v8, v9, v12
	v_mul_f32_e32 v9, v11, v11
	v_fmac_f32_e32 v9, v10, v10
	v_add_f32_e32 v20, v9, v8
	s_waitcnt vmcnt(21)
	v_lshlrev_b32_e32 v8, 16, v88
	v_and_b32_e32 v9, 0xffff0000, v88
	v_cvt_pk_bf16_f32 v19, v10, v11
	v_lshlrev_b32_e32 v10, 16, v89
	v_and_b32_e32 v11, 0xffff0000, v89
	v_pk_fma_f32 v[4:5], v[206:207], v[8:9], v[4:5] op_sel_hi:[0,1,1]
	v_lshlrev_b32_e32 v12, 16, v90
	v_and_b32_e32 v13, 0xffff0000, v90
	v_pk_fma_f32 v[6:7], v[206:207], v[10:11], v[6:7] op_sel_hi:[0,1,1]
	v_cvt_pk_bf16_f32 v8, v4, v5
	v_mul_f32_e32 v5, v5, v5
	v_pk_fma_f32 v[0:1], v[206:207], v[12:13], v[0:1] op_sel_hi:[0,1,1]
	v_fmac_f32_e32 v5, v4, v4
	v_mul_f32_e32 v4, v7, v7
	v_lshlrev_b32_e32 v14, 16, v91
	v_and_b32_e32 v15, 0xffff0000, v91
	v_cvt_pk_bf16_f32 v9, v6, v7
	v_cvt_pk_bf16_f32 v10, v0, v1
	v_fmac_f32_e32 v4, v6, v6
	v_mul_f32_e32 v1, v1, v1
	v_pk_fma_f32 v[2:3], v[206:207], v[14:15], v[2:3] op_sel_hi:[0,1,1]
	v_add_f32_e32 v4, v5, v4
	v_fmac_f32_e32 v1, v0, v0
	v_add_f32_e32 v0, v1, v4
	v_mul_f32_e32 v1, v3, v3
	v_fmac_f32_e32 v1, v2, v2
	v_add_f32_e32 v0, v1, v0
	v_cvt_pk_bf16_f32 v11, v2, v3
	v_add_f32_e32 v4, v20, v0
	v_sub_u32_e32 v0, v204, v233
	v_cndmask_b32_e64 v1, v19, v11, s[6:7]
	ds_bpermute_b32 v15, v219, v4
	v_cndmask_b32_e64 v2, v18, v10, s[6:7]
	v_mov_b32_dpp v14, v1 quad_perm:[1,0,3,2] row_mask:0xf bank_mask:0xf bound_ctrl:1
	v_ashrrev_i32_e32 v1, 31, v0
	v_lshlrev_b64 v[0:1], 11, v[0:1]
	v_cndmask_b32_e64 v3, v17, v9, s[6:7]
	v_cndmask_b32_e64 v5, v16, v8, s[6:7]
	v_lshl_add_u64 v[0:1], s[14:15], 0, v[0:1]
	v_mov_b32_dpp v12, v3 quad_perm:[1,0,3,2] row_mask:0xf bank_mask:0xf bound_ctrl:1
	v_mov_b32_dpp v5, v5 quad_perm:[1,0,3,2] row_mask:0xf bank_mask:0xf bound_ctrl:1
	v_mov_b32_dpp v13, v2 quad_perm:[1,0,3,2] row_mask:0xf bank_mask:0xf bound_ctrl:1
	v_lshl_add_u64 v[0:1], v[202:203], 1, v[0:1]
	v_lshl_add_u64 v[6:7], v[0:1], 0, v[192:193]
	v_cndmask_b32_e64 v0, v5, v16, s[6:7]
	v_cndmask_b32_e64 v1, v12, v17, s[6:7]
	v_cndmask_b32_e64 v2, v13, v18, s[6:7]
	v_cndmask_b32_e64 v3, v14, v19, s[6:7]
	global_store_dwordx4 v[6:7], v[0:3], off
	s_waitcnt lgkmcnt(0)
	s_nop 0
	v_add_f32_e32 v0, v4, v15
	ds_bpermute_b32 v1, v223, v0
	v_cndmask_b32_e64 v2, v8, v5, s[6:7]
	v_cndmask_b32_e64 v3, v9, v12, s[6:7]
	v_cndmask_b32_e64 v4, v10, v13, s[6:7]
	v_cndmask_b32_e64 v5, v11, v14, s[6:7]
	global_store_dwordx4 v[6:7], v[2:5], off offset:2048
	s_and_saveexec_b64 s[42:43], s[0:1]
	s_cbranch_execz .LBB0_665
	v_lshlrev_b64 v[2:3], 6, v[204:205]
	v_lshl_add_u64 v[2:3], s[18:19], 0, v[2:3]
	v_lshl_add_u64 v[2:3], s[40:41], 2, v[2:3]
	s_lshl_b32 s20, s48, 2
	v_lshl_add_u64 v[2:3], v[2:3], 0, s[20:21]
	s_waitcnt lgkmcnt(0)
	v_add_f32_e32 v0, v0, v1
	global_store_dword v[2:3], v0, off

.LBB0_831:
	v_lshl_add_u32 v142, s36, 8, v133
	v_lshl_or_b32 v198, s53, 8, v194
	v_ashrrev_i32_e32 v199, 31, v198
	v_ashrrev_i32_e32 v143, 31, v142
	v_lshl_add_u64 v[144:145], v[198:199], 1, s[14:15]
	v_lshlrev_b64 v[146:147], 11, v[142:143]
	v_lshl_add_u64 v[148:149], v[144:145], 0, v[146:147]
	global_load_dwordx2 v[200:201], v[148:149], off
	global_load_dwordx2 v[202:203], v[148:149], off offset:32
	global_load_dwordx2 v[204:205], v[148:149], off offset:256
	global_load_dwordx2 v[206:207], v[148:149], off offset:288
	v_or_b32_e32 v150, 16, v142
	v_or_b32_e32 v152, 32, v142
	v_or_b32_e32 v154, 48, v142
	v_ashrrev_i32_e32 v151, 31, v150
	v_ashrrev_i32_e32 v153, 31, v152
	v_ashrrev_i32_e32 v155, 31, v154
	v_sub_u32_e32 v146, v142, v193
	v_lshlrev_b64 v[142:143], 11, v[150:151]
	v_lshlrev_b64 v[150:151], 11, v[152:153]
	v_lshlrev_b64 v[152:153], 11, v[154:155]
	v_add_co_u32_e32 v154, vcc, s48, v148
	v_lshl_add_u64 v[142:143], v[144:145], 0, v[142:143]
	s_nop 0
	v_addc_co_u32_e32 v155, vcc, 0, v149, vcc
	v_add_co_u32_e32 v158, vcc, s49, v148
	v_lshl_add_u64 v[150:151], v[144:145], 0, v[150:151]
	s_nop 0
	v_addc_co_u32_e32 v159, vcc, 0, v149, vcc
	v_add_co_u32_e32 v210, vcc, s50, v148
	v_lshl_add_u64 v[144:145], v[144:145], 0, v[152:153]
	s_nop 0
	v_addc_co_u32_e32 v211, vcc, 0, v149, vcc
	v_lshl_add_u64 v[152:153], v[148:149], 0, s[16:17]
	v_lshl_add_u64 v[156:157], v[148:149], 0, s[18:19]
	v_lshl_add_u64 v[208:209], v[148:149], 0, s[20:21]
	v_lshl_add_u64 v[212:213], v[148:149], 0, s[22:23]
	v_add_co_u32_e32 v148, vcc, s51, v148
	v_ashrrev_i32_e32 v147, 31, v146
	s_nop 0
	v_addc_co_u32_e32 v149, vcc, 0, v149, vcc
	global_load_dwordx2 v[214:215], v[142:143], off
	global_load_dwordx2 v[216:217], v[142:143], off offset:32
	global_load_dwordx2 v[218:219], v[142:143], off offset:256
	global_load_dwordx2 v[220:221], v[142:143], off offset:288
	global_load_dwordx2 v[190:191], v[150:151], off
	global_load_dwordx2 v[188:189], v[150:151], off offset:32
	global_load_dwordx2 v[186:187], v[150:151], off offset:256
	global_load_dwordx2 v[184:185], v[150:151], off offset:288
	global_load_dwordx2 v[182:183], v[144:145], off
	global_load_dwordx2 v[180:181], v[144:145], off offset:32
	global_load_dwordx2 v[178:179], v[144:145], off offset:256
	global_load_dwordx2 v[176:177], v[144:145], off offset:288
	global_load_dwordx2 v[174:175], v[154:155], off
	global_load_dwordx2 v[172:173], v[152:153], off offset:32
	global_load_dwordx2 v[170:171], v[152:153], off offset:256
	global_load_dwordx2 v[168:169], v[152:153], off offset:288
	global_load_dwordx2 v[166:167], v[158:159], off
	global_load_dwordx2 v[164:165], v[156:157], off offset:32
	global_load_dwordx2 v[162:163], v[156:157], off offset:256
	global_load_dwordx2 v[160:161], v[156:157], off offset:288
	s_nop 0
	global_load_dwordx2 v[158:159], v[210:211], off
	global_load_dwordx2 v[156:157], v[208:209], off offset:32
	global_load_dwordx2 v[154:155], v[208:209], off offset:256
	global_load_dwordx2 v[152:153], v[208:209], off offset:288
	global_load_dwordx2 v[150:151], v[148:149], off
	s_nop 0
	global_load_dwordx2 v[148:149], v[212:213], off offset:32
	global_load_dwordx2 v[144:145], v[212:213], off offset:256
	global_load_dwordx2 v[142:143], v[212:213], off offset:288
	v_or_b32_e32 v198, v198, v132
	s_waitcnt vmcnt(31)
	v_lshlrev_b32_e32 v208, 16, v200
	v_and_b32_e32 v209, 0xffff0000, v200
	v_lshlrev_b32_e32 v200, 16, v201
	v_and_b32_e32 v201, 0xffff0000, v201
	s_waitcnt vmcnt(30)
	v_lshlrev_b32_e32 v210, 16, v202
	v_and_b32_e32 v211, 0xffff0000, v202
	v_lshlrev_b32_e32 v202, 16, v203
	v_and_b32_e32 v203, 0xffff0000, v203
	v_pk_add_f32 v[208:209], v[124:125], v[208:209]
	v_pk_add_f32 v[124:125], v[126:127], v[200:201]
	v_pk_add_f32 v[200:201], v[122:123], v[202:203]
	v_pk_add_f32 v[126:127], v[120:121], v[210:211]
	v_cndmask_b32_e64 v120, v125, v201, s[0:1]
	v_cndmask_b32_e64 v121, v124, v200, s[0:1]
	v_cndmask_b32_e64 v122, v209, v127, s[0:1]
	v_cndmask_b32_e64 v123, v208, v126, s[0:1]
	v_mov_b32_dpp v212, v121 quad_perm:[1,0,3,2] row_mask:0xf bank_mask:0xf bound_ctrl:1
	v_mov_b32_dpp v213, v120 quad_perm:[1,0,3,2] row_mask:0xf bank_mask:0xf bound_ctrl:1
	v_lshlrev_b64 v[120:121], 12, v[146:147]
	v_mov_b32_dpp v210, v123 quad_perm:[1,0,3,2] row_mask:0xf bank_mask:0xf bound_ctrl:1
	v_mov_b32_dpp v211, v122 quad_perm:[1,0,3,2] row_mask:0xf bank_mask:0xf bound_ctrl:1
	v_lshl_add_u64 v[202:203], s[74:75], 0, v[120:121]
	v_lshlrev_b64 v[120:121], 2, v[198:199]
	v_cndmask_b32_e64 v125, v213, v125, s[0:1]
	v_cndmask_b32_e64 v124, v212, v124, s[0:1]
	v_cndmask_b32_e64 v123, v211, v209, s[0:1]
	v_cndmask_b32_e64 v122, v210, v208, s[0:1]
	v_lshl_add_u64 v[198:199], v[202:203], 0, v[120:121]
	global_store_dwordx4 v[198:199], v[122:125], off nt
	s_nop 1
	v_cndmask_b32_e64 v122, v126, v210, s[0:1]
	v_add_co_u32_e32 v126, vcc, s52, v198
	v_cndmask_b32_e64 v125, v201, v213, s[0:1]
	v_cndmask_b32_e64 v124, v200, v212, s[0:1]
	v_cndmask_b32_e64 v123, v127, v211, s[0:1]
	v_addc_co_u32_e32 v127, vcc, 0, v199, vcc
	global_store_dwordx4 v[126:127], v[122:125], off nt
	s_nop 1
	s_waitcnt vmcnt(31)
	v_lshlrev_b32_e32 v122, 16, v204
	v_and_b32_e32 v123, 0xffff0000, v204
	v_lshlrev_b32_e32 v124, 16, v205
	v_and_b32_e32 v125, 0xffff0000, v205
	v_pk_add_f32 v[116:117], v[116:117], v[122:123]
	v_pk_add_f32 v[118:119], v[118:119], v[124:125]
	s_waitcnt vmcnt(30)
	v_lshlrev_b32_e32 v122, 16, v206
	v_and_b32_e32 v123, 0xffff0000, v206
	v_lshlrev_b32_e32 v124, 16, v207
	v_and_b32_e32 v125, 0xffff0000, v207
	v_pk_add_f32 v[122:123], v[112:113], v[122:123]
	v_pk_add_f32 v[124:125], v[114:115], v[124:125]
	v_cndmask_b32_e64 v114, v117, v123, s[0:1]
	v_cndmask_b32_e64 v112, v119, v125, s[0:1]
	v_cndmask_b32_e64 v113, v118, v124, s[0:1]
	v_cndmask_b32_e64 v115, v116, v122, s[0:1]
	v_mov_b32_dpp v200, v114 quad_perm:[1,0,3,2] row_mask:0xf bank_mask:0xf bound_ctrl:1
	v_mov_b32_dpp v201, v113 quad_perm:[1,0,3,2] row_mask:0xf bank_mask:0xf bound_ctrl:1
	v_mov_b32_dpp v147, v115 quad_perm:[1,0,3,2] row_mask:0xf bank_mask:0xf bound_ctrl:1
	v_mov_b32_dpp v202, v112 quad_perm:[1,0,3,2] row_mask:0xf bank_mask:0xf bound_ctrl:1
	v_cndmask_b32_e64 v115, v202, v119, s[0:1]
	v_cndmask_b32_e64 v114, v201, v118, s[0:1]
	v_cndmask_b32_e64 v113, v200, v117, s[0:1]
	v_cndmask_b32_e64 v112, v147, v116, s[0:1]
	global_store_dwordx4 v[198:199], v[112:115], off offset:512 nt
	s_waitcnt vmcnt(30)
	v_lshlrev_b32_e32 v116, 16, v215
	v_and_b32_e32 v117, 0xffff0000, v215
	v_cndmask_b32_e64 v115, v125, v202, s[0:1]
	v_cndmask_b32_e64 v114, v124, v201, s[0:1]
	v_cndmask_b32_e64 v113, v123, v200, s[0:1]
	v_cndmask_b32_e64 v112, v122, v147, s[0:1]
	global_store_dwordx4 v[126:127], v[112:115], off offset:512 nt
	v_pk_add_f32 v[110:111], v[110:111], v[116:117]
	s_waitcnt vmcnt(30)
	v_lshlrev_b32_e32 v116, 16, v217
	v_lshlrev_b32_e32 v114, 16, v214
	v_and_b32_e32 v115, 0xffff0000, v214
	v_pk_add_f32 v[108:109], v[108:109], v[114:115]
	v_lshlrev_b32_e32 v114, 16, v216
	v_and_b32_e32 v115, 0xffff0000, v216
	v_and_b32_e32 v117, 0xffff0000, v217
	v_pk_add_f32 v[114:115], v[104:105], v[114:115]
	v_add_u32_e32 v112, 16, v146
	v_pk_add_f32 v[116:117], v[106:107], v[116:117]
	v_cndmask_b32_e64 v106, v109, v115, s[0:1]
	v_cndmask_b32_e64 v107, v108, v114, s[0:1]
	v_ashrrev_i32_e32 v113, 31, v112
	v_cndmask_b32_e64 v104, v111, v117, s[0:1]
	v_cndmask_b32_e64 v105, v110, v116, s[0:1]
	v_mov_b32_dpp v118, v107 quad_perm:[1,0,3,2] row_mask:0xf bank_mask:0xf bound_ctrl:1
	v_mov_b32_dpp v119, v106 quad_perm:[1,0,3,2] row_mask:0xf bank_mask:0xf bound_ctrl:1
	v_mov_b32_dpp v122, v105 quad_perm:[1,0,3,2] row_mask:0xf bank_mask:0xf bound_ctrl:1
	v_mov_b32_dpp v123, v104 quad_perm:[1,0,3,2] row_mask:0xf bank_mask:0xf bound_ctrl:1
	v_cndmask_b32_e64 v105, v119, v109, s[0:1]
	v_cndmask_b32_e64 v104, v118, v108, s[0:1]
	v_lshlrev_b64 v[108:109], 12, v[112:113]
	v_lshl_add_u64 v[108:109], s[74:75], 0, v[108:109]
	v_lshl_add_u64 v[108:109], v[108:109], 0, v[120:121]
	v_cndmask_b32_e64 v107, v123, v111, s[0:1]
	v_cndmask_b32_e64 v106, v122, v110, s[0:1]
	v_add_co_u32_e32 v110, vcc, s52, v108
	global_store_dwordx4 v[108:109], v[104:107], off nt
	s_nop 0
	v_addc_co_u32_e32 v111, vcc, 0, v109, vcc
	v_cndmask_b32_e64 v107, v117, v123, s[0:1]
	v_cndmask_b32_e64 v106, v116, v122, s[0:1]
	v_cndmask_b32_e64 v105, v115, v119, s[0:1]
	v_cndmask_b32_e64 v104, v114, v118, s[0:1]
	global_store_dwordx4 v[110:111], v[104:107], off nt
	s_nop 1
	s_waitcnt vmcnt(31)
	v_lshlrev_b32_e32 v104, 16, v218
	v_and_b32_e32 v105, 0xffff0000, v218
	v_lshlrev_b32_e32 v106, 16, v219
	v_and_b32_e32 v107, 0xffff0000, v219
	v_pk_add_f32 v[100:101], v[100:101], v[104:105]
	v_pk_add_f32 v[102:103], v[102:103], v[106:107]
	s_waitcnt vmcnt(30)
	v_lshlrev_b32_e32 v104, 16, v220
	v_and_b32_e32 v105, 0xffff0000, v220
	v_lshlrev_b32_e32 v106, 16, v221
	v_and_b32_e32 v107, 0xffff0000, v221
	v_pk_add_f32 v[104:105], v[96:97], v[104:105]
	v_pk_add_f32 v[106:107], v[98:99], v[106:107]
	v_cndmask_b32_e64 v98, v101, v105, s[0:1]
	v_cndmask_b32_e64 v96, v103, v107, s[0:1]
	v_cndmask_b32_e64 v97, v102, v106, s[0:1]
	v_cndmask_b32_e64 v99, v100, v104, s[0:1]
	v_mov_b32_dpp v113, v98 quad_perm:[1,0,3,2] row_mask:0xf bank_mask:0xf bound_ctrl:1
	v_mov_b32_dpp v114, v97 quad_perm:[1,0,3,2] row_mask:0xf bank_mask:0xf bound_ctrl:1
	v_mov_b32_dpp v112, v99 quad_perm:[1,0,3,2] row_mask:0xf bank_mask:0xf bound_ctrl:1
	v_mov_b32_dpp v115, v96 quad_perm:[1,0,3,2] row_mask:0xf bank_mask:0xf bound_ctrl:1
	v_cndmask_b32_e64 v99, v115, v103, s[0:1]
	v_cndmask_b32_e64 v98, v114, v102, s[0:1]
	v_cndmask_b32_e64 v97, v113, v101, s[0:1]
	v_cndmask_b32_e64 v96, v112, v100, s[0:1]
	global_store_dwordx4 v[108:109], v[96:99], off offset:512 nt
	s_waitcnt vmcnt(30)
	v_lshlrev_b32_e32 v100, 16, v191
	v_and_b32_e32 v101, 0xffff0000, v191
	v_cndmask_b32_e64 v99, v107, v115, s[0:1]
	v_cndmask_b32_e64 v98, v106, v114, s[0:1]
	v_cndmask_b32_e64 v97, v105, v113, s[0:1]
	v_cndmask_b32_e64 v96, v104, v112, s[0:1]
	global_store_dwordx4 v[110:111], v[96:99], off offset:512 nt
	v_pk_add_f32 v[94:95], v[94:95], v[100:101]
	s_waitcnt vmcnt(30)
	v_lshlrev_b32_e32 v100, 16, v189
	v_lshlrev_b32_e32 v98, 16, v190
	v_and_b32_e32 v99, 0xffff0000, v190
	v_pk_add_f32 v[92:93], v[92:93], v[98:99]
	v_lshlrev_b32_e32 v98, 16, v188
	v_and_b32_e32 v99, 0xffff0000, v188
	v_and_b32_e32 v101, 0xffff0000, v189
	v_pk_add_f32 v[98:99], v[88:89], v[98:99]
	v_add_u32_e32 v96, 32, v146
	v_pk_add_f32 v[100:101], v[90:91], v[100:101]
	v_cndmask_b32_e64 v90, v93, v99, s[0:1]
	v_cndmask_b32_e64 v91, v92, v98, s[0:1]
	v_ashrrev_i32_e32 v97, 31, v96
	v_cndmask_b32_e64 v88, v95, v101, s[0:1]
	v_cndmask_b32_e64 v89, v94, v100, s[0:1]
	v_mov_b32_dpp v102, v91 quad_perm:[1,0,3,2] row_mask:0xf bank_mask:0xf bound_ctrl:1
	v_mov_b32_dpp v103, v90 quad_perm:[1,0,3,2] row_mask:0xf bank_mask:0xf bound_ctrl:1
	v_mov_b32_dpp v104, v89 quad_perm:[1,0,3,2] row_mask:0xf bank_mask:0xf bound_ctrl:1
	v_mov_b32_dpp v105, v88 quad_perm:[1,0,3,2] row_mask:0xf bank_mask:0xf bound_ctrl:1
	v_cndmask_b32_e64 v89, v103, v93, s[0:1]
	v_cndmask_b32_e64 v88, v102, v92, s[0:1]
	v_lshlrev_b64 v[92:93], 12, v[96:97]
	v_lshl_add_u64 v[92:93], s[74:75], 0, v[92:93]
	v_lshl_add_u64 v[92:93], v[92:93], 0, v[120:121]
	v_cndmask_b32_e64 v91, v105, v95, s[0:1]
	v_cndmask_b32_e64 v90, v104, v94, s[0:1]
	v_add_co_u32_e32 v94, vcc, s52, v92
	global_store_dwordx4 v[92:93], v[88:91], off nt
	s_nop 0
	v_addc_co_u32_e32 v95, vcc, 0, v93, vcc
	v_cndmask_b32_e64 v91, v101, v105, s[0:1]
	v_cndmask_b32_e64 v90, v100, v104, s[0:1]
	v_cndmask_b32_e64 v89, v99, v103, s[0:1]
	v_cndmask_b32_e64 v88, v98, v102, s[0:1]
	global_store_dwordx4 v[94:95], v[88:91], off nt
	s_nop 1
	s_waitcnt vmcnt(31)
	v_lshlrev_b32_e32 v88, 16, v186
	v_and_b32_e32 v89, 0xffff0000, v186
	v_lshlrev_b32_e32 v90, 16, v187
	v_and_b32_e32 v91, 0xffff0000, v187
	v_pk_add_f32 v[84:85], v[84:85], v[88:89]
	v_pk_add_f32 v[86:87], v[86:87], v[90:91]
	s_waitcnt vmcnt(30)
	v_lshlrev_b32_e32 v88, 16, v184
	v_and_b32_e32 v89, 0xffff0000, v184
	v_lshlrev_b32_e32 v90, 16, v185
	v_and_b32_e32 v91, 0xffff0000, v185
	v_pk_add_f32 v[88:89], v[80:81], v[88:89]
	v_pk_add_f32 v[90:91], v[82:83], v[90:91]
	v_cndmask_b32_e64 v82, v85, v89, s[0:1]
	v_cndmask_b32_e64 v80, v87, v91, s[0:1]
	v_cndmask_b32_e64 v81, v86, v90, s[0:1]
	v_cndmask_b32_e64 v83, v84, v88, s[0:1]
	v_mov_b32_dpp v97, v82 quad_perm:[1,0,3,2] row_mask:0xf bank_mask:0xf bound_ctrl:1
	v_mov_b32_dpp v98, v81 quad_perm:[1,0,3,2] row_mask:0xf bank_mask:0xf bound_ctrl:1
	v_mov_b32_dpp v96, v83 quad_perm:[1,0,3,2] row_mask:0xf bank_mask:0xf bound_ctrl:1
	v_mov_b32_dpp v99, v80 quad_perm:[1,0,3,2] row_mask:0xf bank_mask:0xf bound_ctrl:1
	v_cndmask_b32_e64 v83, v99, v87, s[0:1]
	v_cndmask_b32_e64 v82, v98, v86, s[0:1]
	v_cndmask_b32_e64 v81, v97, v85, s[0:1]
	v_cndmask_b32_e64 v80, v96, v84, s[0:1]
	global_store_dwordx4 v[92:93], v[80:83], off offset:512 nt
	s_waitcnt vmcnt(30)
	v_lshlrev_b32_e32 v84, 16, v183
	v_and_b32_e32 v85, 0xffff0000, v183
	v_cndmask_b32_e64 v83, v91, v99, s[0:1]
	v_cndmask_b32_e64 v82, v90, v98, s[0:1]
	v_cndmask_b32_e64 v81, v89, v97, s[0:1]
	v_cndmask_b32_e64 v80, v88, v96, s[0:1]
	global_store_dwordx4 v[94:95], v[80:83], off offset:512 nt
	v_pk_add_f32 v[78:79], v[78:79], v[84:85]
	s_waitcnt vmcnt(30)
	v_lshlrev_b32_e32 v84, 16, v181
	v_lshlrev_b32_e32 v82, 16, v182
	v_and_b32_e32 v83, 0xffff0000, v182
	v_pk_add_f32 v[76:77], v[76:77], v[82:83]
	v_lshlrev_b32_e32 v82, 16, v180
	v_and_b32_e32 v83, 0xffff0000, v180
	v_and_b32_e32 v85, 0xffff0000, v181
	v_pk_add_f32 v[82:83], v[72:73], v[82:83]
	v_add_u32_e32 v80, 48, v146
	v_pk_add_f32 v[84:85], v[74:75], v[84:85]
	v_cndmask_b32_e64 v74, v77, v83, s[0:1]
	v_cndmask_b32_e64 v75, v76, v82, s[0:1]
	v_ashrrev_i32_e32 v81, 31, v80
	v_cndmask_b32_e64 v72, v79, v85, s[0:1]
	v_cndmask_b32_e64 v73, v78, v84, s[0:1]
	v_mov_b32_dpp v86, v75 quad_perm:[1,0,3,2] row_mask:0xf bank_mask:0xf bound_ctrl:1
	v_mov_b32_dpp v87, v74 quad_perm:[1,0,3,2] row_mask:0xf bank_mask:0xf bound_ctrl:1
	v_mov_b32_dpp v88, v73 quad_perm:[1,0,3,2] row_mask:0xf bank_mask:0xf bound_ctrl:1
	v_mov_b32_dpp v89, v72 quad_perm:[1,0,3,2] row_mask:0xf bank_mask:0xf bound_ctrl:1
	v_cndmask_b32_e64 v73, v87, v77, s[0:1]
	v_cndmask_b32_e64 v72, v86, v76, s[0:1]
	v_lshlrev_b64 v[76:77], 12, v[80:81]
	v_lshl_add_u64 v[76:77], s[74:75], 0, v[76:77]
	v_lshl_add_u64 v[76:77], v[76:77], 0, v[120:121]
	v_cndmask_b32_e64 v75, v89, v79, s[0:1]
	v_cndmask_b32_e64 v74, v88, v78, s[0:1]
	v_add_co_u32_e32 v78, vcc, s52, v76
	global_store_dwordx4 v[76:77], v[72:75], off nt
	s_nop 0
	v_addc_co_u32_e32 v79, vcc, 0, v77, vcc
	v_cndmask_b32_e64 v75, v85, v89, s[0:1]
	v_cndmask_b32_e64 v74, v84, v88, s[0:1]
	v_cndmask_b32_e64 v73, v83, v87, s[0:1]
	v_cndmask_b32_e64 v72, v82, v86, s[0:1]
	global_store_dwordx4 v[78:79], v[72:75], off nt
	s_nop 1
	s_waitcnt vmcnt(31)
	v_lshlrev_b32_e32 v72, 16, v178
	v_and_b32_e32 v73, 0xffff0000, v178
	v_lshlrev_b32_e32 v74, 16, v179
	v_and_b32_e32 v75, 0xffff0000, v179
	v_pk_add_f32 v[68:69], v[68:69], v[72:73]
	v_pk_add_f32 v[70:71], v[70:71], v[74:75]
	s_waitcnt vmcnt(30)
	v_lshlrev_b32_e32 v72, 16, v176
	v_and_b32_e32 v73, 0xffff0000, v176
	v_lshlrev_b32_e32 v74, 16, v177
	v_and_b32_e32 v75, 0xffff0000, v177
	v_pk_add_f32 v[72:73], v[64:65], v[72:73]
	v_pk_add_f32 v[74:75], v[66:67], v[74:75]
	v_cndmask_b32_e64 v66, v69, v73, s[0:1]
	v_cndmask_b32_e64 v64, v71, v75, s[0:1]
	v_cndmask_b32_e64 v65, v70, v74, s[0:1]
	v_cndmask_b32_e64 v67, v68, v72, s[0:1]
	v_mov_b32_dpp v81, v66 quad_perm:[1,0,3,2] row_mask:0xf bank_mask:0xf bound_ctrl:1
	v_mov_b32_dpp v82, v65 quad_perm:[1,0,3,2] row_mask:0xf bank_mask:0xf bound_ctrl:1
	v_mov_b32_dpp v80, v67 quad_perm:[1,0,3,2] row_mask:0xf bank_mask:0xf bound_ctrl:1
	v_mov_b32_dpp v83, v64 quad_perm:[1,0,3,2] row_mask:0xf bank_mask:0xf bound_ctrl:1
	v_cndmask_b32_e64 v67, v83, v71, s[0:1]
	v_cndmask_b32_e64 v66, v82, v70, s[0:1]
	v_cndmask_b32_e64 v65, v81, v69, s[0:1]
	v_cndmask_b32_e64 v64, v80, v68, s[0:1]
	global_store_dwordx4 v[76:77], v[64:67], off offset:512 nt
	s_waitcnt vmcnt(30)
	v_lshlrev_b32_e32 v68, 16, v175
	v_and_b32_e32 v69, 0xffff0000, v175
	v_cndmask_b32_e64 v67, v75, v83, s[0:1]
	v_cndmask_b32_e64 v66, v74, v82, s[0:1]
	v_cndmask_b32_e64 v65, v73, v81, s[0:1]
	v_cndmask_b32_e64 v64, v72, v80, s[0:1]
	global_store_dwordx4 v[78:79], v[64:67], off offset:512 nt
	v_pk_add_f32 v[62:63], v[62:63], v[68:69]
	s_waitcnt vmcnt(30)
	v_lshlrev_b32_e32 v68, 16, v173
	v_lshlrev_b32_e32 v66, 16, v174
	v_and_b32_e32 v67, 0xffff0000, v174
	v_pk_add_f32 v[60:61], v[60:61], v[66:67]
	v_lshlrev_b32_e32 v66, 16, v172
	v_and_b32_e32 v67, 0xffff0000, v172
	v_and_b32_e32 v69, 0xffff0000, v173
	v_pk_add_f32 v[66:67], v[56:57], v[66:67]
	v_add_u32_e32 v64, 0x80, v146
	v_pk_add_f32 v[68:69], v[58:59], v[68:69]
	v_cndmask_b32_e64 v58, v61, v67, s[0:1]
	v_cndmask_b32_e64 v59, v60, v66, s[0:1]
	v_ashrrev_i32_e32 v65, 31, v64
	v_cndmask_b32_e64 v56, v63, v69, s[0:1]
	v_cndmask_b32_e64 v57, v62, v68, s[0:1]
	v_mov_b32_dpp v70, v59 quad_perm:[1,0,3,2] row_mask:0xf bank_mask:0xf bound_ctrl:1
	v_mov_b32_dpp v71, v58 quad_perm:[1,0,3,2] row_mask:0xf bank_mask:0xf bound_ctrl:1
	v_mov_b32_dpp v72, v57 quad_perm:[1,0,3,2] row_mask:0xf bank_mask:0xf bound_ctrl:1
	v_mov_b32_dpp v73, v56 quad_perm:[1,0,3,2] row_mask:0xf bank_mask:0xf bound_ctrl:1
	v_cndmask_b32_e64 v57, v71, v61, s[0:1]
	v_cndmask_b32_e64 v56, v70, v60, s[0:1]
	v_lshlrev_b64 v[60:61], 12, v[64:65]
	v_lshl_add_u64 v[60:61], s[74:75], 0, v[60:61]
	v_lshl_add_u64 v[60:61], v[60:61], 0, v[120:121]
	v_cndmask_b32_e64 v59, v73, v63, s[0:1]
	v_cndmask_b32_e64 v58, v72, v62, s[0:1]
	v_add_co_u32_e32 v62, vcc, s52, v60
	global_store_dwordx4 v[60:61], v[56:59], off nt
	s_nop 0
	v_addc_co_u32_e32 v63, vcc, 0, v61, vcc
	v_cndmask_b32_e64 v59, v69, v73, s[0:1]
	v_cndmask_b32_e64 v58, v68, v72, s[0:1]
	v_cndmask_b32_e64 v57, v67, v71, s[0:1]
	v_cndmask_b32_e64 v56, v66, v70, s[0:1]
	global_store_dwordx4 v[62:63], v[56:59], off nt
	s_nop 1
	s_waitcnt vmcnt(31)
	v_lshlrev_b32_e32 v56, 16, v170
	v_and_b32_e32 v57, 0xffff0000, v170
	v_lshlrev_b32_e32 v58, 16, v171
	v_and_b32_e32 v59, 0xffff0000, v171
	v_pk_add_f32 v[52:53], v[52:53], v[56:57]
	v_pk_add_f32 v[54:55], v[54:55], v[58:59]
	s_waitcnt vmcnt(30)
	v_lshlrev_b32_e32 v56, 16, v168
	v_and_b32_e32 v57, 0xffff0000, v168
	v_lshlrev_b32_e32 v58, 16, v169
	v_and_b32_e32 v59, 0xffff0000, v169
	v_pk_add_f32 v[56:57], v[48:49], v[56:57]
	v_pk_add_f32 v[58:59], v[50:51], v[58:59]
	v_cndmask_b32_e64 v50, v53, v57, s[0:1]
	v_cndmask_b32_e64 v48, v55, v59, s[0:1]
	v_cndmask_b32_e64 v49, v54, v58, s[0:1]
	v_cndmask_b32_e64 v51, v52, v56, s[0:1]
	v_mov_b32_dpp v65, v50 quad_perm:[1,0,3,2] row_mask:0xf bank_mask:0xf bound_ctrl:1
	v_mov_b32_dpp v66, v49 quad_perm:[1,0,3,2] row_mask:0xf bank_mask:0xf bound_ctrl:1
	v_mov_b32_dpp v64, v51 quad_perm:[1,0,3,2] row_mask:0xf bank_mask:0xf bound_ctrl:1
	v_mov_b32_dpp v67, v48 quad_perm:[1,0,3,2] row_mask:0xf bank_mask:0xf bound_ctrl:1
	v_cndmask_b32_e64 v51, v67, v55, s[0:1]
	v_cndmask_b32_e64 v50, v66, v54, s[0:1]
	v_cndmask_b32_e64 v49, v65, v53, s[0:1]
	v_cndmask_b32_e64 v48, v64, v52, s[0:1]
	global_store_dwordx4 v[60:61], v[48:51], off offset:512 nt
	s_waitcnt vmcnt(30)
	v_lshlrev_b32_e32 v52, 16, v167
	v_and_b32_e32 v53, 0xffff0000, v167
	v_cndmask_b32_e64 v51, v59, v67, s[0:1]
	v_cndmask_b32_e64 v50, v58, v66, s[0:1]
	v_cndmask_b32_e64 v49, v57, v65, s[0:1]
	v_cndmask_b32_e64 v48, v56, v64, s[0:1]
	global_store_dwordx4 v[62:63], v[48:51], off offset:512 nt
	v_pk_add_f32 v[46:47], v[46:47], v[52:53]
	s_waitcnt vmcnt(30)
	v_lshlrev_b32_e32 v52, 16, v165
	v_lshlrev_b32_e32 v50, 16, v166
	v_and_b32_e32 v51, 0xffff0000, v166
	v_pk_add_f32 v[44:45], v[44:45], v[50:51]
	v_lshlrev_b32_e32 v50, 16, v164
	v_and_b32_e32 v51, 0xffff0000, v164
	v_and_b32_e32 v53, 0xffff0000, v165
	v_pk_add_f32 v[50:51], v[40:41], v[50:51]
	v_add_u32_e32 v48, 0x90, v146
	v_pk_add_f32 v[52:53], v[42:43], v[52:53]
	v_cndmask_b32_e64 v42, v45, v51, s[0:1]
	v_cndmask_b32_e64 v43, v44, v50, s[0:1]
	v_ashrrev_i32_e32 v49, 31, v48
	v_cndmask_b32_e64 v40, v47, v53, s[0:1]
	v_cndmask_b32_e64 v41, v46, v52, s[0:1]
	v_mov_b32_dpp v54, v43 quad_perm:[1,0,3,2] row_mask:0xf bank_mask:0xf bound_ctrl:1
	v_mov_b32_dpp v55, v42 quad_perm:[1,0,3,2] row_mask:0xf bank_mask:0xf bound_ctrl:1
	v_mov_b32_dpp v56, v41 quad_perm:[1,0,3,2] row_mask:0xf bank_mask:0xf bound_ctrl:1
	v_mov_b32_dpp v57, v40 quad_perm:[1,0,3,2] row_mask:0xf bank_mask:0xf bound_ctrl:1
	v_cndmask_b32_e64 v41, v55, v45, s[0:1]
	v_cndmask_b32_e64 v40, v54, v44, s[0:1]
	v_lshlrev_b64 v[44:45], 12, v[48:49]
	v_lshl_add_u64 v[44:45], s[74:75], 0, v[44:45]
	v_lshl_add_u64 v[44:45], v[44:45], 0, v[120:121]
	v_cndmask_b32_e64 v43, v57, v47, s[0:1]
	v_cndmask_b32_e64 v42, v56, v46, s[0:1]
	v_add_co_u32_e32 v46, vcc, s52, v44
	global_store_dwordx4 v[44:45], v[40:43], off nt
	s_nop 0
	v_addc_co_u32_e32 v47, vcc, 0, v45, vcc
	v_cndmask_b32_e64 v43, v53, v57, s[0:1]
	v_cndmask_b32_e64 v42, v52, v56, s[0:1]
	v_cndmask_b32_e64 v41, v51, v55, s[0:1]
	v_cndmask_b32_e64 v40, v50, v54, s[0:1]
	global_store_dwordx4 v[46:47], v[40:43], off nt
	s_nop 1
	s_waitcnt vmcnt(31)
	v_lshlrev_b32_e32 v40, 16, v162
	v_and_b32_e32 v41, 0xffff0000, v162
	v_lshlrev_b32_e32 v42, 16, v163
	v_and_b32_e32 v43, 0xffff0000, v163
	v_pk_add_f32 v[36:37], v[36:37], v[40:41]
	v_pk_add_f32 v[38:39], v[38:39], v[42:43]
	s_waitcnt vmcnt(30)
	v_lshlrev_b32_e32 v40, 16, v160
	v_and_b32_e32 v41, 0xffff0000, v160
	v_lshlrev_b32_e32 v42, 16, v161
	v_and_b32_e32 v43, 0xffff0000, v161
	v_pk_add_f32 v[40:41], v[32:33], v[40:41]
	v_pk_add_f32 v[42:43], v[34:35], v[42:43]
	v_cndmask_b32_e64 v34, v37, v41, s[0:1]
	v_cndmask_b32_e64 v32, v39, v43, s[0:1]
	v_cndmask_b32_e64 v33, v38, v42, s[0:1]
	v_cndmask_b32_e64 v35, v36, v40, s[0:1]
	v_mov_b32_dpp v49, v34 quad_perm:[1,0,3,2] row_mask:0xf bank_mask:0xf bound_ctrl:1
	v_mov_b32_dpp v50, v33 quad_perm:[1,0,3,2] row_mask:0xf bank_mask:0xf bound_ctrl:1
	v_mov_b32_dpp v48, v35 quad_perm:[1,0,3,2] row_mask:0xf bank_mask:0xf bound_ctrl:1
	v_mov_b32_dpp v51, v32 quad_perm:[1,0,3,2] row_mask:0xf bank_mask:0xf bound_ctrl:1
	v_cndmask_b32_e64 v35, v51, v39, s[0:1]
	v_cndmask_b32_e64 v34, v50, v38, s[0:1]
	v_cndmask_b32_e64 v33, v49, v37, s[0:1]
	v_cndmask_b32_e64 v32, v48, v36, s[0:1]
	global_store_dwordx4 v[44:45], v[32:35], off offset:512 nt
	s_waitcnt vmcnt(30)
	v_lshlrev_b32_e32 v36, 16, v159
	v_and_b32_e32 v37, 0xffff0000, v159
	v_cndmask_b32_e64 v35, v43, v51, s[0:1]
	v_cndmask_b32_e64 v34, v42, v50, s[0:1]
	v_cndmask_b32_e64 v33, v41, v49, s[0:1]
	v_cndmask_b32_e64 v32, v40, v48, s[0:1]
	global_store_dwordx4 v[46:47], v[32:35], off offset:512 nt
	v_pk_add_f32 v[30:31], v[30:31], v[36:37]
	s_waitcnt vmcnt(30)
	v_lshlrev_b32_e32 v36, 16, v157
	v_lshlrev_b32_e32 v34, 16, v158
	v_and_b32_e32 v35, 0xffff0000, v158
	v_pk_add_f32 v[28:29], v[28:29], v[34:35]
	v_lshlrev_b32_e32 v34, 16, v156
	v_and_b32_e32 v35, 0xffff0000, v156
	v_and_b32_e32 v37, 0xffff0000, v157
	v_pk_add_f32 v[34:35], v[24:25], v[34:35]
	v_add_u32_e32 v32, 0xa0, v146
	v_pk_add_f32 v[36:37], v[26:27], v[36:37]
	v_cndmask_b32_e64 v26, v29, v35, s[0:1]
	v_cndmask_b32_e64 v27, v28, v34, s[0:1]
	v_ashrrev_i32_e32 v33, 31, v32
	v_cndmask_b32_e64 v24, v31, v37, s[0:1]
	v_cndmask_b32_e64 v25, v30, v36, s[0:1]
	v_mov_b32_dpp v38, v27 quad_perm:[1,0,3,2] row_mask:0xf bank_mask:0xf bound_ctrl:1
	v_mov_b32_dpp v39, v26 quad_perm:[1,0,3,2] row_mask:0xf bank_mask:0xf bound_ctrl:1
	v_mov_b32_dpp v40, v25 quad_perm:[1,0,3,2] row_mask:0xf bank_mask:0xf bound_ctrl:1
	v_mov_b32_dpp v41, v24 quad_perm:[1,0,3,2] row_mask:0xf bank_mask:0xf bound_ctrl:1
	v_cndmask_b32_e64 v25, v39, v29, s[0:1]
	v_cndmask_b32_e64 v24, v38, v28, s[0:1]
	v_lshlrev_b64 v[28:29], 12, v[32:33]
	v_lshl_add_u64 v[28:29], s[74:75], 0, v[28:29]
	v_lshl_add_u64 v[28:29], v[28:29], 0, v[120:121]
	v_cndmask_b32_e64 v27, v41, v31, s[0:1]
	v_cndmask_b32_e64 v26, v40, v30, s[0:1]
	v_add_co_u32_e32 v30, vcc, s52, v28
	global_store_dwordx4 v[28:29], v[24:27], off nt
	s_nop 0
	v_addc_co_u32_e32 v31, vcc, 0, v29, vcc
	v_cndmask_b32_e64 v27, v37, v41, s[0:1]
	v_cndmask_b32_e64 v26, v36, v40, s[0:1]
	v_cndmask_b32_e64 v25, v35, v39, s[0:1]
	v_cndmask_b32_e64 v24, v34, v38, s[0:1]
	global_store_dwordx4 v[30:31], v[24:27], off nt
	s_nop 1
	s_waitcnt vmcnt(31)
	v_lshlrev_b32_e32 v24, 16, v154
	v_and_b32_e32 v25, 0xffff0000, v154
	v_lshlrev_b32_e32 v26, 16, v155
	v_and_b32_e32 v27, 0xffff0000, v155
	v_pk_add_f32 v[20:21], v[20:21], v[24:25]
	v_pk_add_f32 v[22:23], v[22:23], v[26:27]
	s_waitcnt vmcnt(30)
	v_lshlrev_b32_e32 v24, 16, v152
	v_and_b32_e32 v25, 0xffff0000, v152
	v_lshlrev_b32_e32 v26, 16, v153
	v_and_b32_e32 v27, 0xffff0000, v153
	v_pk_add_f32 v[24:25], v[16:17], v[24:25]
	v_pk_add_f32 v[26:27], v[18:19], v[26:27]
	v_cndmask_b32_e64 v18, v21, v25, s[0:1]
	v_cndmask_b32_e64 v16, v23, v27, s[0:1]
	v_cndmask_b32_e64 v17, v22, v26, s[0:1]
	v_cndmask_b32_e64 v19, v20, v24, s[0:1]
	v_mov_b32_dpp v33, v18 quad_perm:[1,0,3,2] row_mask:0xf bank_mask:0xf bound_ctrl:1
	v_mov_b32_dpp v34, v17 quad_perm:[1,0,3,2] row_mask:0xf bank_mask:0xf bound_ctrl:1
	v_mov_b32_dpp v32, v19 quad_perm:[1,0,3,2] row_mask:0xf bank_mask:0xf bound_ctrl:1
	v_mov_b32_dpp v35, v16 quad_perm:[1,0,3,2] row_mask:0xf bank_mask:0xf bound_ctrl:1
	v_cndmask_b32_e64 v19, v35, v23, s[0:1]
	v_cndmask_b32_e64 v18, v34, v22, s[0:1]
	v_cndmask_b32_e64 v17, v33, v21, s[0:1]
	v_cndmask_b32_e64 v16, v32, v20, s[0:1]
	global_store_dwordx4 v[28:29], v[16:19], off offset:512 nt
	s_waitcnt vmcnt(30)
	v_lshlrev_b32_e32 v20, 16, v151
	v_and_b32_e32 v21, 0xffff0000, v151
	v_cndmask_b32_e64 v19, v27, v35, s[0:1]
	v_cndmask_b32_e64 v18, v26, v34, s[0:1]
	v_cndmask_b32_e64 v17, v25, v33, s[0:1]
	v_cndmask_b32_e64 v16, v24, v32, s[0:1]
	global_store_dwordx4 v[30:31], v[16:19], off offset:512 nt
	v_pk_add_f32 v[14:15], v[14:15], v[20:21]
	s_waitcnt vmcnt(30)
	v_lshlrev_b32_e32 v20, 16, v149
	v_lshlrev_b32_e32 v18, 16, v150
	v_and_b32_e32 v19, 0xffff0000, v150
	v_pk_add_f32 v[12:13], v[12:13], v[18:19]
	v_lshlrev_b32_e32 v18, 16, v148
	v_and_b32_e32 v19, 0xffff0000, v148
	v_and_b32_e32 v21, 0xffff0000, v149
	v_pk_add_f32 v[18:19], v[8:9], v[18:19]
	v_add_u32_e32 v16, 0xb0, v146
	v_pk_add_f32 v[20:21], v[10:11], v[20:21]
	v_cndmask_b32_e64 v10, v13, v19, s[0:1]
	v_cndmask_b32_e64 v11, v12, v18, s[0:1]
	v_ashrrev_i32_e32 v17, 31, v16
	v_cndmask_b32_e64 v8, v15, v21, s[0:1]
	v_cndmask_b32_e64 v9, v14, v20, s[0:1]
	v_mov_b32_dpp v22, v11 quad_perm:[1,0,3,2] row_mask:0xf bank_mask:0xf bound_ctrl:1
	v_mov_b32_dpp v23, v10 quad_perm:[1,0,3,2] row_mask:0xf bank_mask:0xf bound_ctrl:1
	v_mov_b32_dpp v24, v9 quad_perm:[1,0,3,2] row_mask:0xf bank_mask:0xf bound_ctrl:1
	v_mov_b32_dpp v25, v8 quad_perm:[1,0,3,2] row_mask:0xf bank_mask:0xf bound_ctrl:1
	v_cndmask_b32_e64 v9, v23, v13, s[0:1]
	v_cndmask_b32_e64 v8, v22, v12, s[0:1]
	v_lshlrev_b64 v[12:13], 12, v[16:17]
	v_lshl_add_u64 v[12:13], s[74:75], 0, v[12:13]
	v_lshl_add_u64 v[12:13], v[12:13], 0, v[120:121]
	v_cndmask_b32_e64 v11, v25, v15, s[0:1]
	v_cndmask_b32_e64 v10, v24, v14, s[0:1]
	v_add_co_u32_e32 v14, vcc, s52, v12
	global_store_dwordx4 v[12:13], v[8:11], off nt
	s_nop 0
	v_addc_co_u32_e32 v15, vcc, 0, v13, vcc
	v_cndmask_b32_e64 v11, v21, v25, s[0:1]
	v_cndmask_b32_e64 v10, v20, v24, s[0:1]
	v_cndmask_b32_e64 v9, v19, v23, s[0:1]
	v_cndmask_b32_e64 v8, v18, v22, s[0:1]
	global_store_dwordx4 v[14:15], v[8:11], off nt
	s_andn2_b64 vcc, exec, s[4:5]
	s_mov_b64 s[4:5], -1
	s_waitcnt vmcnt(31)
	v_lshlrev_b32_e32 v8, 16, v144
	v_and_b32_e32 v9, 0xffff0000, v144
	v_lshlrev_b32_e32 v10, 16, v145
	v_and_b32_e32 v11, 0xffff0000, v145
	v_pk_add_f32 v[4:5], v[4:5], v[8:9]
	v_pk_add_f32 v[6:7], v[6:7], v[10:11]
	s_waitcnt vmcnt(30)
	v_lshlrev_b32_e32 v8, 16, v142
	v_and_b32_e32 v9, 0xffff0000, v142
	v_lshlrev_b32_e32 v10, 16, v143
	v_and_b32_e32 v11, 0xffff0000, v143
	v_pk_add_f32 v[8:9], v[0:1], v[8:9]
	v_pk_add_f32 v[10:11], v[2:3], v[10:11]
	v_cndmask_b32_e64 v2, v5, v9, s[0:1]
	v_cndmask_b32_e64 v0, v7, v11, s[0:1]
	v_cndmask_b32_e64 v1, v6, v10, s[0:1]
	v_cndmask_b32_e64 v3, v4, v8, s[0:1]
	v_mov_b32_dpp v17, v2 quad_perm:[1,0,3,2] row_mask:0xf bank_mask:0xf bound_ctrl:1
	v_mov_b32_dpp v18, v1 quad_perm:[1,0,3,2] row_mask:0xf bank_mask:0xf bound_ctrl:1
	v_mov_b32_dpp v16, v3 quad_perm:[1,0,3,2] row_mask:0xf bank_mask:0xf bound_ctrl:1
	v_mov_b32_dpp v19, v0 quad_perm:[1,0,3,2] row_mask:0xf bank_mask:0xf bound_ctrl:1
	v_cndmask_b32_e64 v3, v19, v7, s[0:1]
	v_cndmask_b32_e64 v2, v18, v6, s[0:1]
	v_cndmask_b32_e64 v1, v17, v5, s[0:1]
	v_cndmask_b32_e64 v0, v16, v4, s[0:1]
	global_store_dwordx4 v[12:13], v[0:3], off offset:512 nt
	s_nop 1
	v_cndmask_b32_e64 v3, v11, v19, s[0:1]
	v_cndmask_b32_e64 v2, v10, v18, s[0:1]
	v_cndmask_b32_e64 v1, v9, v17, s[0:1]
	v_cndmask_b32_e64 v0, v8, v16, s[0:1]
	global_store_dwordx4 v[14:15], v[0:3], off offset:512 nt
	s_cbranch_vccnz .LBB0_820
	s_andn2_b64 vcc, exec, s[6:7]
	s_cbranch_vccnz .LBB0_819
	s_barrier
	s_branch .LBB0_819
